# loop-head alignment: 64-byte align the hot loop entry labels (NSA tile loops, compressed-branch loops, GEMM DMA loops, RWKV and S5 loops)
# baseline (speedup 1.0000x reference)
.LBB0_56:
	s_lshl_b32 s4, s6, 4
	s_and_b32 s38, s4, 0x7fffff80
	s_lshl_b32 s4, s6, 7
	s_mov_b32 s39, s97
	v_mov_b32_e32 v46, v133
	s_and_b32 s7, s4, 0x380
	s_lshl_b64 s[4:5], s[38:39], 11
	s_add_u32 s46, s88, s4
	v_lshlrev_b32_e32 v0, 3, v46
	v_and_b32_e32 v131, 56, v0
	v_lshlrev_b32_e32 v0, 7, v46
	s_addc_u32 s47, s89, s5
	s_lshl_b32 s4, s7, 11
	v_and_b32_e32 v135, 0xfffffc00, v0
	s_add_u32 s48, s18, s4
	v_or_b32_e32 v0, v131, v135
	v_add_u32_e32 v152, 0x8000, v135
	s_addc_u32 s49, s19, 0
	v_lshlrev_b64 v[2:3], 1, v[0:1]
	v_or_b32_e32 v0, v152, v131
	v_add_u32_e32 v156, 0x10000, v135
	v_lshl_add_u64 v[158:159], s[46:47], 0, v[2:3]
	v_lshl_add_u64 v[160:161], s[48:49], 0, v[2:3]
	v_lshlrev_b64 v[2:3], 1, v[0:1]
	v_or_b32_e32 v0, v156, v131
	v_add_u32_e32 v162, 0x18000, v135
	v_lshl_add_u64 v[34:35], s[46:47], 0, v[2:3]
	v_lshl_add_u64 v[36:37], s[48:49], 0, v[2:3]
	v_lshlrev_b64 v[2:3], 1, v[0:1]
	v_or_b32_e32 v0, v162, v131
	v_lshl_add_u64 v[38:39], s[46:47], 0, v[2:3]
	v_lshl_add_u64 v[40:41], s[48:49], 0, v[2:3]
	v_lshlrev_b64 v[2:3], 1, v[0:1]
	v_lshl_add_u64 v[42:43], s[46:47], 0, v[2:3]
	v_lshl_add_u64 v[44:45], s[48:49], 0, v[2:3]
	v_and_b32_e32 v78, 63, v133
	v_lshrrev_b32_e32 v79, 6, v133
	v_lshlrev_b32_e32 v80, 12, v79
	v_lshrrev_b32_e32 v81, 3, v78
	v_readfirstlane_b32 s4, v80
	v_lshl_add_u32 v81, v79, 5, v81
	v_lshlrev_b32_e32 v81, 11, v81
	v_and_b32_e32 v82, 7, v78
	v_lshrrev_b32_e32 v83, 4, v78
	v_xor_b32_e32 v82, v82, v83
	v_xor_b32_e32 v83, 4, v82
	v_lshl_add_u32 v66, v82, 4, v81
	v_lshl_add_u32 v67, v83, 4, v81
	v_add_u32_e32 v67, 0x4000, v67
	v_add_u32_e32 v68, 0x8000, v66
	v_add_u32_e32 v69, 0x8000, v67
	v_and_b32_e32 v80, 31, v78
	v_lshrrev_b32_e32 v81, 5, v78
	v_bfe_u32 v82, v78, 1, 3
	v_xor_b32_e32 v81, v81, v82
	v_lshrrev_b32_e32 v82, 1, v79
	v_and_b32_e32 v83, 1, v79
	v_lshl_add_u32 v82, v82, 6, v80
	v_lshl_add_u32 v83, v83, 6, v80
	v_lshlrev_b32_e32 v82, 7, v82
	v_lshlrev_b32_e32 v83, 7, v83
	v_add_u32_e32 v83, 0x4000, v83
	v_lshl_add_u32 v70, v81, 4, v82
	v_lshl_add_u32 v74, v81, 4, v83
	v_xor_b32_e32 v84, 2, v81
	v_lshl_add_u32 v71, v84, 4, v82
	v_lshl_add_u32 v75, v84, 4, v83
	v_xor_b32_e32 v84, 4, v81
	v_lshl_add_u32 v72, v84, 4, v82
	v_lshl_add_u32 v76, v84, 4, v83
	v_xor_b32_e32 v84, 6, v81
	v_lshl_add_u32 v73, v84, 4, v82
	v_lshl_add_u32 v77, v84, 4, v83
	s_waitcnt lgkmcnt(0)
	s_barrier
	s_add_u32 m0, s4, 0x0
	s_nop 0
	global_load_lds_dwordx4 v66, s[46:47]
	s_add_u32 m0, s4, 0x400
	s_nop 0
	global_load_lds_dwordx4 v67, s[46:47]
	s_add_u32 m0, s4, 0x800
	s_nop 0
	global_load_lds_dwordx4 v68, s[46:47]
	s_add_u32 m0, s4, 0xc00
	s_nop 0
	global_load_lds_dwordx4 v69, s[46:47]
	s_add_u32 m0, s4, 0x4000
	s_nop 0
	global_load_lds_dwordx4 v66, s[48:49]
	s_add_u32 m0, s4, 0x4400
	s_nop 0
	global_load_lds_dwordx4 v67, s[48:49]
	s_add_u32 m0, s4, 0x4800
	s_nop 0
	global_load_lds_dwordx4 v68, s[48:49]
	s_add_u32 m0, s4, 0x4c00
	s_nop 0
	global_load_lds_dwordx4 v69, s[48:49]
	v_add_u32_e32 v66, 0x80, v66
	v_add_u32_e32 v67, 0x80, v67
	v_add_u32_e32 v68, 0x80, v68
	v_add_u32_e32 v69, 0x80, v69
	v_mov_b32_e32 v2, 0
	v_mov_b32_e32 v3, 0
	v_mov_b32_e32 v4, 0
	v_mov_b32_e32 v5, 0
	v_mov_b32_e32 v6, 0
	v_mov_b32_e32 v7, 0
	v_mov_b32_e32 v8, 0
	v_mov_b32_e32 v9, 0
	v_mov_b32_e32 v10, 0
	v_mov_b32_e32 v11, 0
	v_mov_b32_e32 v12, 0
	v_mov_b32_e32 v13, 0
	v_mov_b32_e32 v14, 0
	v_mov_b32_e32 v15, 0
	v_mov_b32_e32 v16, 0
	v_mov_b32_e32 v17, 0
	v_mov_b32_e32 v18, 0
	v_mov_b32_e32 v19, 0
	v_mov_b32_e32 v20, 0
	v_mov_b32_e32 v21, 0
	v_mov_b32_e32 v22, 0
	v_mov_b32_e32 v23, 0
	v_mov_b32_e32 v24, 0
	v_mov_b32_e32 v25, 0
	v_mov_b32_e32 v26, 0
	v_mov_b32_e32 v27, 0
	v_mov_b32_e32 v28, 0
	v_mov_b32_e32 v29, 0
	v_mov_b32_e32 v30, 0
	v_mov_b32_e32 v31, 0
	v_mov_b32_e32 v32, 0
	v_mov_b32_e32 v33, 0
	v_mov_b32_e32 v34, 0
	v_mov_b32_e32 v35, 0
	v_mov_b32_e32 v36, 0
	v_mov_b32_e32 v37, 0
	v_mov_b32_e32 v38, 0
	v_mov_b32_e32 v39, 0
	v_mov_b32_e32 v40, 0
	v_mov_b32_e32 v41, 0
	v_mov_b32_e32 v42, 0
	v_mov_b32_e32 v43, 0
	v_mov_b32_e32 v44, 0
	v_mov_b32_e32 v45, 0
	v_mov_b32_e32 v46, 0
	v_mov_b32_e32 v47, 0
	v_mov_b32_e32 v48, 0
	v_mov_b32_e32 v49, 0
	v_mov_b32_e32 v50, 0
	v_mov_b32_e32 v51, 0
	v_mov_b32_e32 v52, 0
	v_mov_b32_e32 v53, 0
	v_mov_b32_e32 v54, 0
	v_mov_b32_e32 v55, 0
	v_mov_b32_e32 v56, 0
	v_mov_b32_e32 v57, 0
	v_mov_b32_e32 v58, 0
	v_mov_b32_e32 v59, 0
	v_mov_b32_e32 v60, 0
	v_mov_b32_e32 v61, 0
	v_mov_b32_e32 v62, 0
	v_mov_b32_e32 v63, 0
	v_mov_b32_e32 v64, 0
	v_mov_b32_e32 v65, 0
	s_mov_b32 s8, 0
	s_waitcnt vmcnt(0)
	.p2alignl 6, 3212836864

.LBB0_105:
	v_mov_b32_e32 v3, v133
	s_lshl_b32 s6, s12, 20
	v_lshlrev_b32_e32 v0, 3, v3
	v_lshrrev_b32_e32 v4, 3, v3
	v_and_b32_e32 v156, 56, v0
	v_mul_lo_u32 v4, v4, s21
	v_add_lshl_u32 v168, v4, v156, 1
	v_add_u32_e32 v4, 0x100, v3
	v_lshrrev_b32_e32 v4, 3, v4
	v_mul_lo_u32 v4, v4, s21
	v_add_lshl_u32 v169, v4, v156, 1
	v_add_u32_e32 v4, 0x200, v3
	v_lshrrev_b32_e32 v4, 3, v4
	v_mul_lo_u32 v4, v4, s21
	v_add_lshl_u32 v170, v4, v156, 1
	v_add_u32_e32 v4, 0x300, v3
	v_lshrrev_b32_e32 v4, 3, v4
	v_mul_lo_u32 v4, v4, s21
	s_add_i32 s4, s11, s6
	v_and_b32_e32 v2, 31, v3
	v_lshlrev_b32_e32 v0, 7, v3
	v_add_lshl_u32 v171, v4, v156, 1
	v_lshrrev_b32_e32 v4, 1, v3
	s_mov_b32 s14, 0xfffffc0
	s_lshl_b32 s4, s4, 1
	v_and_b32_e32 v164, 0xfffffc00, v0
	v_and_or_b32 v5, v4, s14, v2
	v_and_b32_e32 v2, 16, v4
	s_add_u32 s4, s18, s4
	v_add_u32_e32 v165, 0x8000, v164
	v_add_u32_e32 v166, 0x10000, v164
	v_add_u32_e32 v167, 0x18000, v164
	v_mad_u64_u32 v[158:159], s[14:15], v5, s37, v[2:3]
	v_and_b32_e32 v3, 0x5f, v3
	s_mov_b32 s7, 1
	s_addc_u32 s5, s19, 0
	v_or_b32_e32 v0, v165, v156
	v_or_b32_e32 v160, v166, v156
	v_or_b32_e32 v162, v167, v156
	v_mad_u32_u24 v159, v3, s37, v2
	v_mov_b32_e32 v161, v156
	v_mov_b32_e32 v2, 0
	v_mov_b32_e32 v3, v152
	v_mov_b32_e32 v4, v152
	v_mov_b32_e32 v5, v152
	v_mov_b32_e32 v6, v152
	v_mov_b32_e32 v7, v152
	v_mov_b32_e32 v8, v152
	v_mov_b32_e32 v9, v152
	v_mov_b32_e32 v10, v152
	v_mov_b32_e32 v11, v152
	v_mov_b32_e32 v12, v152
	v_mov_b32_e32 v13, v152
	v_mov_b32_e32 v14, v152
	v_mov_b32_e32 v15, v152
	v_mov_b32_e32 v16, v152
	v_mov_b32_e32 v17, v152
	v_mov_b32_e32 v18, 0
	v_mov_b32_e32 v19, v152
	v_mov_b32_e32 v20, v152
	v_mov_b32_e32 v21, v152
	v_mov_b32_e32 v22, v152
	v_mov_b32_e32 v23, v152
	v_mov_b32_e32 v24, v152
	v_mov_b32_e32 v25, v152
	v_mov_b32_e32 v26, v152
	v_mov_b32_e32 v27, v152
	v_mov_b32_e32 v28, v152
	v_mov_b32_e32 v29, v152
	v_mov_b32_e32 v30, v152
	v_mov_b32_e32 v31, v152
	v_mov_b32_e32 v32, v152
	v_mov_b32_e32 v33, v152
	v_mov_b32_e32 v34, 0
	v_mov_b32_e32 v35, v152
	v_mov_b32_e32 v36, v152
	v_mov_b32_e32 v37, v152
	v_mov_b32_e32 v38, v152
	v_mov_b32_e32 v39, v152
	v_mov_b32_e32 v40, v152
	v_mov_b32_e32 v41, v152
	v_mov_b32_e32 v42, v152
	v_mov_b32_e32 v43, v152
	v_mov_b32_e32 v44, v152
	v_mov_b32_e32 v45, v152
	v_mov_b32_e32 v46, v152
	v_mov_b32_e32 v47, v152
	v_mov_b32_e32 v48, v152
	v_mov_b32_e32 v49, v152
	s_waitcnt vmcnt(3)
	v_mov_b32_e32 v50, 0
	s_waitcnt vmcnt(2)
	v_mov_b32_e32 v51, v152
	v_mov_b32_e32 v52, v152
	s_waitcnt vmcnt(1)
	v_mov_b32_e32 v53, v152
	v_mov_b32_e32 v54, v152
	v_mov_b32_e32 v55, v152
	v_mov_b32_e32 v56, v152
	v_mov_b32_e32 v57, v152
	v_mov_b32_e32 v58, v152
	v_mov_b32_e32 v59, v152
	v_mov_b32_e32 v60, v152
	v_mov_b32_e32 v61, v152
	v_mov_b32_e32 v62, v152
	v_mov_b32_e32 v63, v152
	v_mov_b32_e32 v64, v152
	v_mov_b32_e32 v65, v152
	v_and_b32_e32 v180, 63, v133
	v_lshrrev_b32_e32 v181, 6, v133
	v_lshlrev_b32_e32 v182, 12, v181
	v_lshrrev_b32_e32 v183, 3, v180
	v_readfirstlane_b32 s14, v182
	v_lshl_add_u32 v183, v181, 5, v183
	v_lshlrev_b32_e32 v183, 11, v183
	v_and_b32_e32 v214, 7, v180
	v_lshrrev_b32_e32 v215, 4, v180
	v_xor_b32_e32 v214, v214, v215
	v_xor_b32_e32 v215, 4, v214
	v_lshl_add_u32 v160, v214, 4, v183
	v_lshl_add_u32 v161, v215, 4, v183
	v_add_u32_e32 v161, 0x4000, v161
	v_add_u32_e32 v162, 0x8000, v160
	v_add_u32_e32 v163, 0x8000, v161
	v_and_b32_e32 v214, 31, v180
	v_lshrrev_b32_e32 v215, 5, v180
	v_bfe_u32 v232, v180, 1, 3
	v_xor_b32_e32 v215, v215, v232
	v_lshrrev_b32_e32 v233, 1, v181
	v_and_b32_e32 v234, 1, v181
	v_lshl_add_u32 v233, v233, 6, v214
	v_lshl_add_u32 v234, v234, 6, v214
	v_lshlrev_b32_e32 v233, 7, v233
	v_lshlrev_b32_e32 v234, 7, v234
	v_add_u32_e32 v234, 0x4000, v234
	v_lshl_add_u32 v172, v215, 4, v233
	v_lshl_add_u32 v176, v215, 4, v234
	v_xor_b32_e32 v235, 2, v215
	v_lshl_add_u32 v173, v235, 4, v233
	v_lshl_add_u32 v177, v235, 4, v234
	v_xor_b32_e32 v235, 4, v215
	v_lshl_add_u32 v174, v235, 4, v233
	v_lshl_add_u32 v178, v235, 4, v234
	v_xor_b32_e32 v235, 6, v215
	v_lshl_add_u32 v175, v235, 4, v233
	v_lshl_add_u32 v179, v235, 4, v234
	s_waitcnt lgkmcnt(0)
	s_barrier
	s_add_u32 m0, s14, 0x0
	s_nop 0
	global_load_lds_dwordx4 v160, s[38:39]
	s_add_u32 m0, s14, 0x400
	s_nop 0
	global_load_lds_dwordx4 v161, s[38:39]
	s_add_u32 m0, s14, 0x800
	s_nop 0
	global_load_lds_dwordx4 v162, s[38:39]
	s_add_u32 m0, s14, 0xc00
	s_nop 0
	global_load_lds_dwordx4 v163, s[38:39]
	s_add_u32 m0, s14, 0x4000
	s_nop 0
	global_load_lds_dwordx4 v160, s[4:5]
	s_add_u32 m0, s14, 0x4400
	s_nop 0
	global_load_lds_dwordx4 v161, s[4:5]
	s_add_u32 m0, s14, 0x4800
	s_nop 0
	global_load_lds_dwordx4 v162, s[4:5]
	s_add_u32 m0, s14, 0x4c00
	s_nop 0
	global_load_lds_dwordx4 v163, s[4:5]
	v_add_u32_e32 v160, 0x80, v160
	v_add_u32_e32 v161, 0x80, v161
	v_add_u32_e32 v162, 0x80, v162
	v_add_u32_e32 v163, 0x80, v163
	s_mov_b32 s7, 0
	s_waitcnt vmcnt(0)
	.p2alignl 6, 3212836864

.Lmgd_skip:
	ds_read_b128 v[236:239], v172 offset:32768
	ds_read_b128 v[244:247], v176 offset:32768
	ds_read_b128 v[248:251], v176 offset:36864
	ds_read_b128 v[240:243], v172 offset:36864
	s_waitcnt lgkmcnt(2)
	v_mfma_f32_32x32x16_bf16 v[50:65], v[236:239], v[244:247], v[50:65]
	s_waitcnt lgkmcnt(1)
	v_mfma_f32_32x32x16_bf16 v[34:49], v[236:239], v[248:251], v[34:49]
	ds_read_b128 v[236:239], v173 offset:32768
	s_waitcnt lgkmcnt(1)
	v_mfma_f32_32x32x16_bf16 v[18:33], v[240:243], v[244:247], v[18:33]
	ds_read_b128 v[244:247], v177 offset:32768
	v_mfma_f32_32x32x16_bf16 v[2:17], v[240:243], v[248:251], v[2:17]
	ds_read_b128 v[248:251], v177 offset:36864
	ds_read_b128 v[240:243], v173 offset:36864
	s_waitcnt lgkmcnt(2)
	v_mfma_f32_32x32x16_bf16 v[50:65], v[236:239], v[244:247], v[50:65]
	s_waitcnt lgkmcnt(1)
	v_mfma_f32_32x32x16_bf16 v[34:49], v[236:239], v[248:251], v[34:49]
	ds_read_b128 v[236:239], v174 offset:32768
	s_waitcnt lgkmcnt(1)
	v_mfma_f32_32x32x16_bf16 v[18:33], v[240:243], v[244:247], v[18:33]
	ds_read_b128 v[244:247], v178 offset:32768
	v_mfma_f32_32x32x16_bf16 v[2:17], v[240:243], v[248:251], v[2:17]
	ds_read_b128 v[248:251], v178 offset:36864
	ds_read_b128 v[240:243], v174 offset:36864
	s_waitcnt lgkmcnt(2)
	v_mfma_f32_32x32x16_bf16 v[50:65], v[236:239], v[244:247], v[50:65]
	s_waitcnt lgkmcnt(1)
	v_mfma_f32_32x32x16_bf16 v[34:49], v[236:239], v[248:251], v[34:49]
	ds_read_b128 v[236:239], v175 offset:32768
	s_waitcnt lgkmcnt(1)
	v_mfma_f32_32x32x16_bf16 v[18:33], v[240:243], v[244:247], v[18:33]
	ds_read_b128 v[244:247], v179 offset:32768
	v_mfma_f32_32x32x16_bf16 v[2:17], v[240:243], v[248:251], v[2:17]
	ds_read_b128 v[248:251], v179 offset:36864
	ds_read_b128 v[240:243], v175 offset:36864
	s_waitcnt lgkmcnt(2)
	v_mfma_f32_32x32x16_bf16 v[50:65], v[236:239], v[244:247], v[50:65]
	s_waitcnt lgkmcnt(1)
	v_mfma_f32_32x32x16_bf16 v[34:49], v[236:239], v[248:251], v[34:49]
	s_waitcnt lgkmcnt(0)
	v_mfma_f32_32x32x16_bf16 v[18:33], v[240:243], v[244:247], v[18:33]
	v_mfma_f32_32x32x16_bf16 v[2:17], v[240:243], v[248:251], v[2:17]
	s_waitcnt vmcnt(0)
	s_add_i32 s7, s7, 1
	s_cmp_lg_u32 s7, 8
	s_cbranch_scc1 .Lmgd_loop
	s_barrier
	s_nop 15
	s_nop 6
	v_mul_f32_e32 v0, 0xbfb8aa3b, v50
	v_exp_f32_e32 v50, v0
	v_mul_f32_e32 v0, 0xbfb8aa3b, v51
	v_exp_f32_e32 v51, v0
	v_mul_f32_e32 v52, 0xbfb8aa3b, v52
	v_mul_f32_e32 v53, 0xbfb8aa3b, v53
	v_exp_f32_e32 v52, v52
	v_pk_add_f32 v[50:51], v[50:51], 1.0 op_sel_hi:[1,0]
	v_exp_f32_e32 v53, v53
	v_div_scale_f32 v0, s[4:5], v51, v51, 1.0
	v_rcp_f32_e32 v156, v0
	v_div_scale_f32 v158, vcc, 1.0, v51, 1.0
	v_pk_add_f32 v[52:53], v[52:53], 1.0 op_sel_hi:[1,0]
	v_fma_f32 v159, -v0, v156, 1.0
	v_fmac_f32_e32 v156, v159, v156
	v_mul_f32_e32 v159, v158, v156
	v_fma_f32 v160, -v0, v159, v158
	v_fmac_f32_e32 v159, v160, v156
	v_fma_f32 v0, -v0, v159, v158
	v_div_scale_f32 v158, s[4:5], v50, v50, 1.0
	v_rcp_f32_e32 v160, v158
	v_div_fmas_f32 v0, v0, v156, v159
	v_div_fixup_f32 v0, v0, v51, 1.0
	v_mul_f32_e32 v34, 0xbfb8aa3b, v34
	v_fma_f32 v51, -v158, v160, 1.0
	v_fmac_f32_e32 v160, v51, v160
	v_div_scale_f32 v51, vcc, 1.0, v50, 1.0
	v_mul_f32_e32 v156, v51, v160
	v_fma_f32 v159, -v158, v156, v51
	v_fmac_f32_e32 v156, v159, v160
	v_fma_f32 v51, -v158, v156, v51
	v_div_scale_f32 v158, s[4:5], v53, v53, 1.0
	v_rcp_f32_e32 v159, v158
	v_div_fmas_f32 v51, v51, v160, v156
	v_div_fixup_f32 v50, v51, v50, 1.0
	v_cvt_pk_bf16_f32 v0, v50, v0
	v_fma_f32 v50, -v158, v159, 1.0
	v_fmac_f32_e32 v159, v50, v159
	v_div_scale_f32 v50, vcc, 1.0, v53, 1.0
	v_mul_f32_e32 v51, v50, v159
	v_fma_f32 v156, -v158, v51, v50
	v_fmac_f32_e32 v51, v156, v159
	v_div_scale_f32 v156, s[4:5], v52, v52, 1.0
	v_fma_f32 v50, -v158, v51, v50
	v_rcp_f32_e32 v158, v156
	v_div_fmas_f32 v50, v50, v159, v51
	v_div_fixup_f32 v53, v50, v53, 1.0
	v_div_scale_f32 v159, vcc, 1.0, v52, 1.0
	v_fma_f32 v50, -v156, v158, 1.0
	v_fmac_f32_e32 v158, v50, v158
	v_mul_f32_e32 v160, v159, v158
	v_fma_f32 v50, -v156, v160, v159
	v_fmac_f32_e32 v160, v50, v158
	v_mul_f32_e32 v50, 0xbfb8aa3b, v54
	v_mul_f32_e32 v51, 0xbfb8aa3b, v55
	v_exp_f32_e32 v50, v50
	v_exp_f32_e32 v51, v51
	v_fma_f32 v54, -v156, v160, v159
	v_div_fmas_f32 v54, v54, v158, v160
	v_div_fixup_f32 v52, v54, v52, 1.0
	v_pk_add_f32 v[50:51], v[50:51], 1.0 op_sel_hi:[1,0]
	v_cvt_pk_bf16_f32 v52, v52, v53
	v_div_scale_f32 v55, s[4:5], v51, v51, 1.0
	v_rcp_f32_e32 v156, v55
	v_mov_b32_e32 v215, v0
	v_mov_b32_e32 v216, v52
	v_div_scale_f32 v54, s[4:5], v50, v50, 1.0
	v_fma_f32 v0, -v55, v156, 1.0
	v_fmac_f32_e32 v156, v0, v156
	v_div_scale_f32 v0, vcc, 1.0, v51, 1.0
	v_mul_f32_e32 v52, v0, v156
	v_fma_f32 v53, -v55, v52, v0
	v_fmac_f32_e32 v52, v53, v156
	v_fma_f32 v0, -v55, v52, v0
	v_rcp_f32_e32 v55, v54
	v_div_fmas_f32 v0, v0, v156, v52
	v_mul_f32_e32 v52, 0xbfb8aa3b, v56
	v_mul_f32_e32 v53, 0xbfb8aa3b, v57
	v_div_fixup_f32 v0, v0, v51, 1.0
	v_fma_f32 v51, -v54, v55, 1.0
	v_exp_f32_e32 v52, v52
	v_exp_f32_e32 v53, v53
	v_fmac_f32_e32 v55, v51, v55
	v_div_scale_f32 v51, vcc, 1.0, v50, 1.0
	v_mul_f32_e32 v156, v51, v55
	v_fma_f32 v56, -v54, v156, v51
	v_fmac_f32_e32 v156, v56, v55
	v_pk_add_f32 v[52:53], v[52:53], 1.0 op_sel_hi:[1,0]
	v_fma_f32 v51, -v54, v156, v51
	v_div_scale_f32 v54, s[4:5], v53, v53, 1.0
	v_rcp_f32_e32 v56, v54
	v_div_fmas_f32 v51, v51, v55, v156
	v_div_fixup_f32 v50, v51, v50, 1.0
	v_cvt_pk_bf16_f32 v0, v50, v0
	v_fma_f32 v50, -v54, v56, 1.0
	v_fmac_f32_e32 v56, v50, v56
	v_div_scale_f32 v50, vcc, 1.0, v53, 1.0
	v_mul_f32_e32 v51, v50, v56
	v_fma_f32 v55, -v54, v51, v50
	v_fmac_f32_e32 v51, v55, v56
	v_fma_f32 v50, -v54, v51, v50
	v_div_scale_f32 v54, s[4:5], v52, v52, 1.0
	v_rcp_f32_e32 v55, v54
	v_div_fmas_f32 v50, v50, v56, v51
	v_div_fixup_f32 v53, v50, v53, 1.0
	v_div_scale_f32 v56, vcc, 1.0, v52, 1.0
	v_fma_f32 v50, -v54, v55, 1.0
	v_fmac_f32_e32 v55, v50, v55
	v_mul_f32_e32 v57, v56, v55
	v_fma_f32 v50, -v54, v57, v56
	v_fmac_f32_e32 v57, v50, v55
	v_mul_f32_e32 v50, 0xbfb8aa3b, v58
	v_mul_f32_e32 v51, 0xbfb8aa3b, v59
	v_exp_f32_e32 v50, v50
	v_exp_f32_e32 v51, v51
	v_fma_f32 v54, -v54, v57, v56
	v_div_fmas_f32 v54, v54, v55, v57
	v_div_fixup_f32 v52, v54, v52, 1.0
	v_pk_add_f32 v[50:51], v[50:51], 1.0 op_sel_hi:[1,0]
	v_cvt_pk_bf16_f32 v52, v52, v53
	v_div_scale_f32 v55, s[4:5], v51, v51, 1.0
	v_rcp_f32_e32 v56, v55
	v_mov_b32_e32 v217, v0
	v_mov_b32_e32 v218, v52
	v_div_scale_f32 v54, s[4:5], v50, v50, 1.0
	v_fma_f32 v0, -v55, v56, 1.0
	v_fmac_f32_e32 v56, v0, v56
	v_div_scale_f32 v0, vcc, 1.0, v51, 1.0
	v_mul_f32_e32 v52, v0, v56
	v_fma_f32 v53, -v55, v52, v0
	v_fmac_f32_e32 v52, v53, v56
	v_fma_f32 v0, -v55, v52, v0
	v_rcp_f32_e32 v55, v54
	v_div_fmas_f32 v0, v0, v56, v52
	v_mul_f32_e32 v52, 0xbfb8aa3b, v60
	v_mul_f32_e32 v53, 0xbfb8aa3b, v61
	v_div_fixup_f32 v0, v0, v51, 1.0
	v_fma_f32 v51, -v54, v55, 1.0
	v_exp_f32_e32 v52, v52
	v_exp_f32_e32 v53, v53
	v_fmac_f32_e32 v55, v51, v55
	v_div_scale_f32 v51, vcc, 1.0, v50, 1.0
	v_mul_f32_e32 v56, v51, v55
	v_fma_f32 v57, -v54, v56, v51
	v_fmac_f32_e32 v56, v57, v55
	v_pk_add_f32 v[52:53], v[52:53], 1.0 op_sel_hi:[1,0]
	v_fma_f32 v51, -v54, v56, v51
	v_div_scale_f32 v54, s[4:5], v53, v53, 1.0
	v_rcp_f32_e32 v57, v54
	v_div_fmas_f32 v51, v51, v55, v56
	v_div_fixup_f32 v50, v51, v50, 1.0
	v_cvt_pk_bf16_f32 v0, v50, v0
	v_fma_f32 v50, -v54, v57, 1.0
	v_fmac_f32_e32 v57, v50, v57
	v_div_scale_f32 v50, vcc, 1.0, v53, 1.0
	v_mul_f32_e32 v51, v50, v57
	v_fma_f32 v55, -v54, v51, v50
	v_fmac_f32_e32 v51, v55, v57
	v_fma_f32 v50, -v54, v51, v50
	v_div_scale_f32 v54, s[4:5], v52, v52, 1.0
	v_rcp_f32_e32 v55, v54
	v_div_fmas_f32 v50, v50, v57, v51
	v_div_fixup_f32 v53, v50, v53, 1.0
	v_div_scale_f32 v56, vcc, 1.0, v52, 1.0
	v_fma_f32 v50, -v54, v55, 1.0
	v_fmac_f32_e32 v55, v50, v55
	v_mul_f32_e32 v57, v56, v55
	v_fma_f32 v50, -v54, v57, v56
	v_fmac_f32_e32 v57, v50, v55
	v_mul_f32_e32 v50, 0xbfb8aa3b, v62
	v_mul_f32_e32 v51, 0xbfb8aa3b, v63
	v_exp_f32_e32 v50, v50
	v_exp_f32_e32 v51, v51
	v_fma_f32 v54, -v54, v57, v56
	v_div_fmas_f32 v54, v54, v55, v57
	v_div_fixup_f32 v52, v54, v52, 1.0
	v_pk_add_f32 v[50:51], v[50:51], 1.0 op_sel_hi:[1,0]
	v_cvt_pk_bf16_f32 v52, v52, v53
	v_div_scale_f32 v55, s[4:5], v51, v51, 1.0
	v_rcp_f32_e32 v56, v55
	v_mov_b32_e32 v219, v0
	v_mov_b32_e32 v220, v52
	v_div_scale_f32 v54, s[4:5], v50, v50, 1.0
	v_fma_f32 v0, -v55, v56, 1.0
	v_fmac_f32_e32 v56, v0, v56
	v_div_scale_f32 v0, vcc, 1.0, v51, 1.0
	v_mul_f32_e32 v52, v0, v56
	v_fma_f32 v53, -v55, v52, v0
	v_fmac_f32_e32 v52, v53, v56
	v_fma_f32 v0, -v55, v52, v0
	v_rcp_f32_e32 v55, v54
	v_div_fmas_f32 v0, v0, v56, v52
	v_mul_f32_e32 v52, 0xbfb8aa3b, v64
	v_mul_f32_e32 v53, 0xbfb8aa3b, v65
	v_div_fixup_f32 v0, v0, v51, 1.0
	v_fma_f32 v51, -v54, v55, 1.0
	v_exp_f32_e32 v52, v52
	v_exp_f32_e32 v53, v53
	v_fmac_f32_e32 v55, v51, v55
	v_div_scale_f32 v51, vcc, 1.0, v50, 1.0
	v_mul_f32_e32 v56, v51, v55
	v_fma_f32 v57, -v54, v56, v51
	v_fmac_f32_e32 v56, v57, v55
	v_pk_add_f32 v[52:53], v[52:53], 1.0 op_sel_hi:[1,0]
	v_fma_f32 v51, -v54, v56, v51
	v_div_scale_f32 v54, s[4:5], v53, v53, 1.0
	v_rcp_f32_e32 v57, v54
	v_div_fmas_f32 v51, v51, v55, v56
	v_div_fixup_f32 v50, v51, v50, 1.0
	v_cvt_pk_bf16_f32 v0, v50, v0
	v_fma_f32 v50, -v54, v57, 1.0
	v_fmac_f32_e32 v57, v50, v57
	v_div_scale_f32 v50, vcc, 1.0, v53, 1.0
	v_mul_f32_e32 v51, v50, v57
	v_fma_f32 v55, -v54, v51, v50
	v_fmac_f32_e32 v51, v55, v57
	v_fma_f32 v50, -v54, v51, v50
	v_div_scale_f32 v54, s[4:5], v52, v52, 1.0
	v_rcp_f32_e32 v55, v54
	v_div_fmas_f32 v50, v50, v57, v51
	v_mul_f32_e32 v35, 0xbfb8aa3b, v35
	v_exp_f32_e32 v34, v34
	v_fma_f32 v51, -v54, v55, 1.0
	v_fmac_f32_e32 v55, v51, v55
	v_div_scale_f32 v51, vcc, 1.0, v52, 1.0
	v_exp_f32_e32 v35, v35
	v_div_fixup_f32 v50, v50, v53, 1.0
	v_mul_f32_e32 v53, v51, v55
	v_fma_f32 v56, -v54, v53, v51
	v_fmac_f32_e32 v53, v56, v55
	v_fma_f32 v51, -v54, v53, v51
	v_pk_add_f32 v[34:35], v[34:35], 1.0 op_sel_hi:[1,0]
	v_div_fmas_f32 v51, v51, v55, v53
	v_div_scale_f32 v53, s[4:5], v35, v35, 1.0
	v_rcp_f32_e32 v54, v53
	v_div_fixup_f32 v51, v51, v52, 1.0
	v_cvt_pk_bf16_f32 v50, v51, v50
	v_mov_b32_e32 v221, v0
	v_mov_b32_e32 v222, v50
	v_fma_f32 v0, -v53, v54, 1.0
	v_fmac_f32_e32 v54, v0, v54
	v_div_scale_f32 v0, vcc, 1.0, v35, 1.0
	v_mul_f32_e32 v50, v0, v54
	v_fma_f32 v51, -v53, v50, v0
	v_fmac_f32_e32 v50, v51, v54
	v_div_scale_f32 v51, s[4:5], v34, v34, 1.0
	v_rcp_f32_e32 v52, v51
	v_fma_f32 v0, -v53, v50, v0
	v_div_fmas_f32 v0, v0, v54, v50
	v_mul_f32_e32 v36, 0xbfb8aa3b, v36
	v_mul_f32_e32 v37, 0xbfb8aa3b, v37
	v_div_fixup_f32 v0, v0, v35, 1.0
	v_fma_f32 v35, -v51, v52, 1.0
	v_exp_f32_e32 v36, v36
	v_exp_f32_e32 v37, v37
	v_fmac_f32_e32 v52, v35, v52
	v_div_scale_f32 v35, vcc, 1.0, v34, 1.0
	v_mul_f32_e32 v50, v35, v52
	v_fma_f32 v53, -v51, v50, v35
	v_fmac_f32_e32 v50, v53, v52
	v_pk_add_f32 v[36:37], v[36:37], 1.0 op_sel_hi:[1,0]
	v_fma_f32 v35, -v51, v50, v35
	v_div_scale_f32 v51, s[4:5], v37, v37, 1.0
	v_rcp_f32_e32 v53, v51
	v_div_fmas_f32 v35, v35, v52, v50
	v_div_fixup_f32 v34, v35, v34, 1.0
	v_cvt_pk_bf16_f32 v0, v34, v0
	v_fma_f32 v34, -v51, v53, 1.0
	v_fmac_f32_e32 v53, v34, v53
	v_div_scale_f32 v34, vcc, 1.0, v37, 1.0
	v_mul_f32_e32 v35, v34, v53
	v_fma_f32 v50, -v51, v35, v34
	v_fmac_f32_e32 v35, v50, v53
	v_div_scale_f32 v50, s[4:5], v36, v36, 1.0
	v_fma_f32 v34, -v51, v35, v34
	v_rcp_f32_e32 v51, v50
	v_div_fmas_f32 v34, v34, v53, v35
	v_div_fixup_f32 v37, v34, v37, 1.0
	v_div_scale_f32 v52, vcc, 1.0, v36, 1.0
	v_fma_f32 v34, -v50, v51, 1.0
	v_fmac_f32_e32 v51, v34, v51
	v_mul_f32_e32 v53, v52, v51
	v_fma_f32 v34, -v50, v53, v52
	v_fmac_f32_e32 v53, v34, v51
	v_mul_f32_e32 v34, 0xbfb8aa3b, v38
	v_mul_f32_e32 v35, 0xbfb8aa3b, v39
	v_exp_f32_e32 v34, v34
	v_exp_f32_e32 v35, v35
	v_fma_f32 v38, -v50, v53, v52
	v_div_fmas_f32 v38, v38, v51, v53
	v_div_fixup_f32 v36, v38, v36, 1.0
	v_pk_add_f32 v[34:35], v[34:35], 1.0 op_sel_hi:[1,0]
	v_cvt_pk_bf16_f32 v36, v36, v37
	v_div_scale_f32 v39, s[4:5], v35, v35, 1.0
	v_rcp_f32_e32 v50, v39
	v_mov_b32_e32 v223, v0
	v_mov_b32_e32 v224, v36
	v_div_scale_f32 v38, s[4:5], v34, v34, 1.0
	v_fma_f32 v0, -v39, v50, 1.0
	v_fmac_f32_e32 v50, v0, v50
	v_div_scale_f32 v0, vcc, 1.0, v35, 1.0
	v_mul_f32_e32 v36, v0, v50
	v_fma_f32 v37, -v39, v36, v0
	v_fmac_f32_e32 v36, v37, v50
	v_fma_f32 v0, -v39, v36, v0
	v_rcp_f32_e32 v39, v38
	v_div_fmas_f32 v0, v0, v50, v36
	v_mul_f32_e32 v36, 0xbfb8aa3b, v40
	v_mul_f32_e32 v37, 0xbfb8aa3b, v41
	v_div_fixup_f32 v0, v0, v35, 1.0
	v_fma_f32 v35, -v38, v39, 1.0
	v_exp_f32_e32 v36, v36
	v_exp_f32_e32 v37, v37
	v_fmac_f32_e32 v39, v35, v39
	v_div_scale_f32 v35, vcc, 1.0, v34, 1.0
	v_mul_f32_e32 v50, v35, v39
	v_fma_f32 v40, -v38, v50, v35
	v_fmac_f32_e32 v50, v40, v39
	v_pk_add_f32 v[36:37], v[36:37], 1.0 op_sel_hi:[1,0]
	v_fma_f32 v35, -v38, v50, v35
	v_div_scale_f32 v38, s[4:5], v37, v37, 1.0
	v_rcp_f32_e32 v40, v38
	v_div_fmas_f32 v35, v35, v39, v50
	v_div_fixup_f32 v34, v35, v34, 1.0
	v_cvt_pk_bf16_f32 v0, v34, v0
	v_fma_f32 v34, -v38, v40, 1.0
	v_fmac_f32_e32 v40, v34, v40
	v_div_scale_f32 v34, vcc, 1.0, v37, 1.0
	v_mul_f32_e32 v35, v34, v40
	v_fma_f32 v39, -v38, v35, v34
	v_fmac_f32_e32 v35, v39, v40
	v_fma_f32 v34, -v38, v35, v34
	v_div_scale_f32 v38, s[4:5], v36, v36, 1.0
	v_rcp_f32_e32 v39, v38
	v_div_fmas_f32 v34, v34, v40, v35
	v_div_fixup_f32 v37, v34, v37, 1.0
	v_div_scale_f32 v40, vcc, 1.0, v36, 1.0
	v_fma_f32 v34, -v38, v39, 1.0
	v_fmac_f32_e32 v39, v34, v39
	v_mul_f32_e32 v41, v40, v39
	v_fma_f32 v34, -v38, v41, v40
	v_fmac_f32_e32 v41, v34, v39
	v_mul_f32_e32 v34, 0xbfb8aa3b, v42
	v_mul_f32_e32 v35, 0xbfb8aa3b, v43
	v_exp_f32_e32 v34, v34
	v_exp_f32_e32 v35, v35
	v_fma_f32 v38, -v38, v41, v40
	v_div_fmas_f32 v38, v38, v39, v41
	v_div_fixup_f32 v36, v38, v36, 1.0
	v_pk_add_f32 v[34:35], v[34:35], 1.0 op_sel_hi:[1,0]
	v_cvt_pk_bf16_f32 v36, v36, v37
	v_div_scale_f32 v39, s[4:5], v35, v35, 1.0
	v_rcp_f32_e32 v40, v39
	v_mov_b32_e32 v225, v0
	v_mov_b32_e32 v226, v36
	v_div_scale_f32 v38, s[4:5], v34, v34, 1.0
	v_fma_f32 v0, -v39, v40, 1.0
	v_fmac_f32_e32 v40, v0, v40
	v_div_scale_f32 v0, vcc, 1.0, v35, 1.0
	v_mul_f32_e32 v36, v0, v40
	v_fma_f32 v37, -v39, v36, v0
	v_fmac_f32_e32 v36, v37, v40
	v_fma_f32 v0, -v39, v36, v0
	v_rcp_f32_e32 v39, v38
	v_div_fmas_f32 v0, v0, v40, v36
	v_mul_f32_e32 v36, 0xbfb8aa3b, v44
	v_mul_f32_e32 v37, 0xbfb8aa3b, v45
	v_div_fixup_f32 v0, v0, v35, 1.0
	v_fma_f32 v35, -v38, v39, 1.0
	v_exp_f32_e32 v36, v36
	v_exp_f32_e32 v37, v37
	v_fmac_f32_e32 v39, v35, v39
	v_div_scale_f32 v35, vcc, 1.0, v34, 1.0
	v_mul_f32_e32 v40, v35, v39
	v_fma_f32 v41, -v38, v40, v35
	v_fmac_f32_e32 v40, v41, v39
	v_pk_add_f32 v[36:37], v[36:37], 1.0 op_sel_hi:[1,0]
	v_fma_f32 v35, -v38, v40, v35
	v_div_scale_f32 v38, s[4:5], v37, v37, 1.0
	v_rcp_f32_e32 v41, v38
	v_div_fmas_f32 v35, v35, v39, v40
	v_div_fixup_f32 v34, v35, v34, 1.0
	v_cvt_pk_bf16_f32 v0, v34, v0
	v_fma_f32 v34, -v38, v41, 1.0
	v_fmac_f32_e32 v41, v34, v41
	v_div_scale_f32 v34, vcc, 1.0, v37, 1.0
	v_mul_f32_e32 v35, v34, v41
	v_fma_f32 v39, -v38, v35, v34
	v_fmac_f32_e32 v35, v39, v41
	v_fma_f32 v34, -v38, v35, v34
	v_div_scale_f32 v38, s[4:5], v36, v36, 1.0
	v_rcp_f32_e32 v39, v38
	v_div_fmas_f32 v34, v34, v41, v35
	v_div_fixup_f32 v37, v34, v37, 1.0
	v_div_scale_f32 v40, vcc, 1.0, v36, 1.0
	v_fma_f32 v34, -v38, v39, 1.0
	v_fmac_f32_e32 v39, v34, v39
	v_mul_f32_e32 v41, v40, v39
	v_fma_f32 v34, -v38, v41, v40
	v_fmac_f32_e32 v41, v34, v39
	v_mul_f32_e32 v34, 0xbfb8aa3b, v46
	v_mul_f32_e32 v35, 0xbfb8aa3b, v47
	v_exp_f32_e32 v34, v34
	v_exp_f32_e32 v35, v35
	v_fma_f32 v38, -v38, v41, v40
	v_div_fmas_f32 v38, v38, v39, v41
	v_div_fixup_f32 v36, v38, v36, 1.0
	v_pk_add_f32 v[34:35], v[34:35], 1.0 op_sel_hi:[1,0]
	v_cvt_pk_bf16_f32 v36, v36, v37
	v_div_scale_f32 v39, s[4:5], v35, v35, 1.0
	v_rcp_f32_e32 v40, v39
	v_mov_b32_e32 v227, v0
	v_mov_b32_e32 v228, v36
	v_div_scale_f32 v38, s[4:5], v34, v34, 1.0
	v_fma_f32 v0, -v39, v40, 1.0
	v_fmac_f32_e32 v40, v0, v40
	v_div_scale_f32 v0, vcc, 1.0, v35, 1.0
	v_mul_f32_e32 v36, v0, v40
	v_fma_f32 v37, -v39, v36, v0
	v_fmac_f32_e32 v36, v37, v40
	v_fma_f32 v0, -v39, v36, v0
	v_rcp_f32_e32 v39, v38
	v_div_fmas_f32 v0, v0, v40, v36
	v_mul_f32_e32 v36, 0xbfb8aa3b, v48
	v_mul_f32_e32 v37, 0xbfb8aa3b, v49
	v_div_fixup_f32 v0, v0, v35, 1.0
	v_fma_f32 v35, -v38, v39, 1.0
	v_exp_f32_e32 v36, v36
	v_exp_f32_e32 v37, v37
	v_fmac_f32_e32 v39, v35, v39
	v_div_scale_f32 v35, vcc, 1.0, v34, 1.0
	v_mul_f32_e32 v40, v35, v39
	v_fma_f32 v41, -v38, v40, v35
	v_fmac_f32_e32 v40, v41, v39
	v_pk_add_f32 v[36:37], v[36:37], 1.0 op_sel_hi:[1,0]
	v_fma_f32 v35, -v38, v40, v35
	v_div_scale_f32 v38, s[4:5], v37, v37, 1.0
	v_rcp_f32_e32 v41, v38
	v_div_fmas_f32 v35, v35, v39, v40
	v_div_fixup_f32 v34, v35, v34, 1.0
	v_cvt_pk_bf16_f32 v0, v34, v0
	v_fma_f32 v34, -v38, v41, 1.0
	v_fmac_f32_e32 v41, v34, v41
	v_div_scale_f32 v34, vcc, 1.0, v37, 1.0
	v_mul_f32_e32 v35, v34, v41
	v_fma_f32 v39, -v38, v35, v34
	v_fmac_f32_e32 v35, v39, v41
	v_fma_f32 v34, -v38, v35, v34
	v_div_scale_f32 v38, s[4:5], v36, v36, 1.0
	v_rcp_f32_e32 v39, v38
	v_div_fmas_f32 v34, v34, v41, v35
	v_mul_f32_e32 v18, 0xbfb8aa3b, v18
	v_mul_f32_e32 v19, 0xbfb8aa3b, v19
	v_fma_f32 v35, -v38, v39, 1.0
	v_fmac_f32_e32 v39, v35, v39
	v_div_scale_f32 v35, vcc, 1.0, v36, 1.0
	v_exp_f32_e32 v18, v18
	v_exp_f32_e32 v19, v19
	v_div_fixup_f32 v34, v34, v37, 1.0
	v_mul_f32_e32 v37, v35, v39
	v_fma_f32 v40, -v38, v37, v35
	v_fmac_f32_e32 v37, v40, v39
	v_fma_f32 v35, -v38, v37, v35
	v_pk_add_f32 v[18:19], v[18:19], 1.0 op_sel_hi:[1,0]
	v_div_fmas_f32 v35, v35, v39, v37
	v_div_scale_f32 v37, s[4:5], v19, v19, 1.0
	v_rcp_f32_e32 v38, v37
	v_div_fixup_f32 v35, v35, v36, 1.0
	v_cvt_pk_bf16_f32 v34, v35, v34
	v_mov_b32_e32 v229, v0
	v_mov_b32_e32 v230, v34
	v_fma_f32 v0, -v37, v38, 1.0
	v_fmac_f32_e32 v38, v0, v38
	v_div_scale_f32 v0, vcc, 1.0, v19, 1.0
	v_mul_f32_e32 v34, v0, v38
	v_fma_f32 v35, -v37, v34, v0
	v_fmac_f32_e32 v34, v35, v38
	v_div_scale_f32 v35, s[4:5], v18, v18, 1.0
	v_rcp_f32_e32 v36, v35
	v_fma_f32 v0, -v37, v34, v0
	v_div_fmas_f32 v0, v0, v38, v34
	v_mul_f32_e32 v20, 0xbfb8aa3b, v20
	v_mul_f32_e32 v21, 0xbfb8aa3b, v21
	v_div_fixup_f32 v0, v0, v19, 1.0
	v_fma_f32 v19, -v35, v36, 1.0
	v_exp_f32_e32 v20, v20
	v_exp_f32_e32 v21, v21
	v_fmac_f32_e32 v36, v19, v36
	v_div_scale_f32 v19, vcc, 1.0, v18, 1.0
	v_mul_f32_e32 v34, v19, v36
	v_fma_f32 v37, -v35, v34, v19
	v_fmac_f32_e32 v34, v37, v36
	v_pk_add_f32 v[20:21], v[20:21], 1.0 op_sel_hi:[1,0]
	v_fma_f32 v19, -v35, v34, v19
	v_div_scale_f32 v35, s[4:5], v21, v21, 1.0
	v_rcp_f32_e32 v37, v35
	v_div_fmas_f32 v19, v19, v36, v34
	v_div_fixup_f32 v18, v19, v18, 1.0
	v_cvt_pk_bf16_f32 v0, v18, v0
	v_fma_f32 v18, -v35, v37, 1.0
	v_fmac_f32_e32 v37, v18, v37
	v_div_scale_f32 v18, vcc, 1.0, v21, 1.0
	v_mul_f32_e32 v19, v18, v37
	v_fma_f32 v34, -v35, v19, v18
	v_fmac_f32_e32 v19, v34, v37
	v_div_scale_f32 v34, s[4:5], v20, v20, 1.0
	v_fma_f32 v18, -v35, v19, v18
	v_rcp_f32_e32 v35, v34
	v_div_fmas_f32 v18, v18, v37, v19
	v_div_fixup_f32 v21, v18, v21, 1.0
	v_div_scale_f32 v36, vcc, 1.0, v20, 1.0
	v_fma_f32 v18, -v34, v35, 1.0
	v_fmac_f32_e32 v35, v18, v35
	v_mul_f32_e32 v37, v36, v35
	v_fma_f32 v18, -v34, v37, v36
	v_fmac_f32_e32 v37, v18, v35
	v_mul_f32_e32 v18, 0xbfb8aa3b, v22
	v_mul_f32_e32 v19, 0xbfb8aa3b, v23
	v_exp_f32_e32 v18, v18
	v_exp_f32_e32 v19, v19
	v_fma_f32 v22, -v34, v37, v36
	v_div_fmas_f32 v22, v22, v35, v37
	v_div_fixup_f32 v20, v22, v20, 1.0
	v_pk_add_f32 v[18:19], v[18:19], 1.0 op_sel_hi:[1,0]
	v_cvt_pk_bf16_f32 v20, v20, v21
	v_div_scale_f32 v23, s[4:5], v19, v19, 1.0
	v_rcp_f32_e32 v34, v23
	v_mov_b32_e32 v231, v0
	v_mov_b32_e32 v232, v20
	v_div_scale_f32 v22, s[4:5], v18, v18, 1.0
	v_fma_f32 v0, -v23, v34, 1.0
	v_fmac_f32_e32 v34, v0, v34
	v_div_scale_f32 v0, vcc, 1.0, v19, 1.0
	v_mul_f32_e32 v20, v0, v34
	v_fma_f32 v21, -v23, v20, v0
	v_fmac_f32_e32 v20, v21, v34
	v_fma_f32 v0, -v23, v20, v0
	v_rcp_f32_e32 v23, v22
	v_div_fmas_f32 v0, v0, v34, v20
	v_mul_f32_e32 v20, 0xbfb8aa3b, v24
	v_mul_f32_e32 v21, 0xbfb8aa3b, v25
	v_div_fixup_f32 v0, v0, v19, 1.0
	v_fma_f32 v19, -v22, v23, 1.0
	v_exp_f32_e32 v20, v20
	v_exp_f32_e32 v21, v21
	v_fmac_f32_e32 v23, v19, v23
	v_div_scale_f32 v19, vcc, 1.0, v18, 1.0
	v_mul_f32_e32 v34, v19, v23
	v_fma_f32 v24, -v22, v34, v19
	v_fmac_f32_e32 v34, v24, v23
	v_pk_add_f32 v[20:21], v[20:21], 1.0 op_sel_hi:[1,0]
	v_fma_f32 v19, -v22, v34, v19
	v_div_scale_f32 v22, s[4:5], v21, v21, 1.0
	v_rcp_f32_e32 v24, v22
	v_div_fmas_f32 v19, v19, v23, v34
	v_div_fixup_f32 v18, v19, v18, 1.0
	v_cvt_pk_bf16_f32 v0, v18, v0
	v_fma_f32 v18, -v22, v24, 1.0
	v_fmac_f32_e32 v24, v18, v24
	v_div_scale_f32 v18, vcc, 1.0, v21, 1.0
	v_mul_f32_e32 v19, v18, v24
	v_fma_f32 v23, -v22, v19, v18
	v_fmac_f32_e32 v19, v23, v24
	v_fma_f32 v18, -v22, v19, v18
	v_div_scale_f32 v22, s[4:5], v20, v20, 1.0
	v_rcp_f32_e32 v23, v22
	v_div_fmas_f32 v18, v18, v24, v19
	v_div_fixup_f32 v21, v18, v21, 1.0
	v_div_scale_f32 v24, vcc, 1.0, v20, 1.0
	v_fma_f32 v18, -v22, v23, 1.0
	v_fmac_f32_e32 v23, v18, v23
	v_mul_f32_e32 v25, v24, v23
	v_fma_f32 v18, -v22, v25, v24
	v_fmac_f32_e32 v25, v18, v23
	v_mul_f32_e32 v18, 0xbfb8aa3b, v26
	v_mul_f32_e32 v19, 0xbfb8aa3b, v27
	v_exp_f32_e32 v18, v18
	v_exp_f32_e32 v19, v19
	v_fma_f32 v22, -v22, v25, v24
	v_div_fmas_f32 v22, v22, v23, v25
	v_div_fixup_f32 v20, v22, v20, 1.0
	v_pk_add_f32 v[18:19], v[18:19], 1.0 op_sel_hi:[1,0]
	v_cvt_pk_bf16_f32 v20, v20, v21
	v_div_scale_f32 v23, s[4:5], v19, v19, 1.0
	v_rcp_f32_e32 v24, v23
	v_mov_b32_e32 v233, v0
	v_mov_b32_e32 v234, v20
	v_div_scale_f32 v22, s[4:5], v18, v18, 1.0
	v_fma_f32 v0, -v23, v24, 1.0
	v_fmac_f32_e32 v24, v0, v24
	v_div_scale_f32 v0, vcc, 1.0, v19, 1.0
	v_mul_f32_e32 v20, v0, v24
	v_fma_f32 v21, -v23, v20, v0
	v_fmac_f32_e32 v20, v21, v24
	v_fma_f32 v0, -v23, v20, v0
	v_rcp_f32_e32 v23, v22
	v_div_fmas_f32 v0, v0, v24, v20
	v_mul_f32_e32 v20, 0xbfb8aa3b, v28
	v_mul_f32_e32 v21, 0xbfb8aa3b, v29
	v_div_fixup_f32 v0, v0, v19, 1.0
	v_fma_f32 v19, -v22, v23, 1.0
	v_exp_f32_e32 v20, v20
	v_exp_f32_e32 v21, v21
	v_fmac_f32_e32 v23, v19, v23
	v_div_scale_f32 v19, vcc, 1.0, v18, 1.0
	v_mul_f32_e32 v24, v19, v23
	v_fma_f32 v25, -v22, v24, v19
	v_fmac_f32_e32 v24, v25, v23
	v_pk_add_f32 v[20:21], v[20:21], 1.0 op_sel_hi:[1,0]
	v_fma_f32 v19, -v22, v24, v19
	v_div_scale_f32 v22, s[4:5], v21, v21, 1.0
	v_rcp_f32_e32 v25, v22
	v_div_fmas_f32 v19, v19, v23, v24
	v_div_fixup_f32 v18, v19, v18, 1.0
	v_cvt_pk_bf16_f32 v0, v18, v0
	v_fma_f32 v18, -v22, v25, 1.0
	v_fmac_f32_e32 v25, v18, v25
	v_div_scale_f32 v18, vcc, 1.0, v21, 1.0
	v_mul_f32_e32 v19, v18, v25
	v_fma_f32 v23, -v22, v19, v18
	v_fmac_f32_e32 v19, v23, v25
	v_fma_f32 v18, -v22, v19, v18
	v_div_scale_f32 v22, s[4:5], v20, v20, 1.0
	v_rcp_f32_e32 v23, v22
	v_div_fmas_f32 v18, v18, v25, v19
	v_div_fixup_f32 v21, v18, v21, 1.0
	v_div_scale_f32 v24, vcc, 1.0, v20, 1.0
	v_fma_f32 v18, -v22, v23, 1.0
	v_fmac_f32_e32 v23, v18, v23
	v_mul_f32_e32 v25, v24, v23
	v_fma_f32 v18, -v22, v25, v24
	v_fmac_f32_e32 v25, v18, v23
	v_mul_f32_e32 v18, 0xbfb8aa3b, v30
	v_mul_f32_e32 v19, 0xbfb8aa3b, v31
	v_exp_f32_e32 v18, v18
	v_exp_f32_e32 v19, v19
	v_fma_f32 v22, -v22, v25, v24
	v_div_fmas_f32 v22, v22, v23, v25
	v_div_fixup_f32 v20, v22, v20, 1.0
	v_pk_add_f32 v[18:19], v[18:19], 1.0 op_sel_hi:[1,0]
	v_cvt_pk_bf16_f32 v20, v20, v21
	v_div_scale_f32 v23, s[4:5], v19, v19, 1.0
	v_rcp_f32_e32 v24, v23
	v_mov_b32_e32 v235, v0
	v_mov_b32_e32 v174, v20
	v_div_scale_f32 v22, s[4:5], v18, v18, 1.0
	v_fma_f32 v0, -v23, v24, 1.0
	v_fmac_f32_e32 v24, v0, v24
	v_div_scale_f32 v0, vcc, 1.0, v19, 1.0
	v_mul_f32_e32 v20, v0, v24
	v_fma_f32 v21, -v23, v20, v0
	v_fmac_f32_e32 v20, v21, v24
	v_fma_f32 v0, -v23, v20, v0
	v_rcp_f32_e32 v23, v22
	v_div_fmas_f32 v0, v0, v24, v20
	v_mul_f32_e32 v20, 0xbfb8aa3b, v32
	v_mul_f32_e32 v21, 0xbfb8aa3b, v33
	v_div_fixup_f32 v0, v0, v19, 1.0
	v_fma_f32 v19, -v22, v23, 1.0
	v_exp_f32_e32 v20, v20
	v_exp_f32_e32 v21, v21
	v_fmac_f32_e32 v23, v19, v23
	v_div_scale_f32 v19, vcc, 1.0, v18, 1.0
	v_mul_f32_e32 v24, v19, v23
	v_fma_f32 v25, -v22, v24, v19
	v_fmac_f32_e32 v24, v25, v23
	v_pk_add_f32 v[20:21], v[20:21], 1.0 op_sel_hi:[1,0]
	v_fma_f32 v19, -v22, v24, v19
	v_div_scale_f32 v22, s[4:5], v21, v21, 1.0
	v_rcp_f32_e32 v25, v22
	v_div_fmas_f32 v19, v19, v23, v24
	v_div_fixup_f32 v18, v19, v18, 1.0
	v_cvt_pk_bf16_f32 v0, v18, v0
	v_fma_f32 v18, -v22, v25, 1.0
	v_fmac_f32_e32 v25, v18, v25
	v_div_scale_f32 v18, vcc, 1.0, v21, 1.0
	v_mul_f32_e32 v19, v18, v25
	v_fma_f32 v23, -v22, v19, v18
	v_fmac_f32_e32 v19, v23, v25
	v_fma_f32 v18, -v22, v19, v18
	v_div_scale_f32 v22, s[4:5], v20, v20, 1.0
	v_rcp_f32_e32 v23, v22
	v_div_fmas_f32 v18, v18, v25, v19
	v_mul_f32_e32 v2, 0xbfb8aa3b, v2
	v_mul_f32_e32 v3, 0xbfb8aa3b, v3
	v_fma_f32 v19, -v22, v23, 1.0
	v_fmac_f32_e32 v23, v19, v23
	v_div_scale_f32 v19, vcc, 1.0, v20, 1.0
	v_exp_f32_e32 v2, v2
	v_exp_f32_e32 v3, v3
	v_div_fixup_f32 v18, v18, v21, 1.0
	v_mul_f32_e32 v21, v19, v23
	v_fma_f32 v24, -v22, v21, v19
	v_fmac_f32_e32 v21, v24, v23
	v_fma_f32 v19, -v22, v21, v19
	v_pk_add_f32 v[2:3], v[2:3], 1.0 op_sel_hi:[1,0]
	v_div_fmas_f32 v19, v19, v23, v21
	v_div_scale_f32 v21, s[4:5], v3, v3, 1.0
	v_rcp_f32_e32 v22, v21
	v_div_fixup_f32 v19, v19, v20, 1.0
	v_cvt_pk_bf16_f32 v18, v19, v18
	v_mov_b32_e32 v175, v0
	v_mov_b32_e32 v176, v18
	v_fma_f32 v0, -v21, v22, 1.0
	v_fmac_f32_e32 v22, v0, v22
	v_div_scale_f32 v0, vcc, 1.0, v3, 1.0
	v_mul_f32_e32 v18, v0, v22
	v_fma_f32 v19, -v21, v18, v0
	v_fmac_f32_e32 v18, v19, v22
	v_div_scale_f32 v19, s[4:5], v2, v2, 1.0
	v_rcp_f32_e32 v20, v19
	v_fma_f32 v0, -v21, v18, v0
	v_div_fmas_f32 v0, v0, v22, v18
	v_mul_f32_e32 v4, 0xbfb8aa3b, v4
	v_mul_f32_e32 v5, 0xbfb8aa3b, v5
	v_div_fixup_f32 v0, v0, v3, 1.0
	v_fma_f32 v3, -v19, v20, 1.0
	v_exp_f32_e32 v4, v4
	v_exp_f32_e32 v5, v5
	v_fmac_f32_e32 v20, v3, v20
	v_div_scale_f32 v3, vcc, 1.0, v2, 1.0
	v_mul_f32_e32 v18, v3, v20
	v_fma_f32 v21, -v19, v18, v3
	v_fmac_f32_e32 v18, v21, v20
	v_pk_add_f32 v[4:5], v[4:5], 1.0 op_sel_hi:[1,0]
	v_fma_f32 v3, -v19, v18, v3
	v_div_scale_f32 v19, s[4:5], v5, v5, 1.0
	v_rcp_f32_e32 v21, v19
	v_div_fmas_f32 v3, v3, v20, v18
	v_div_fixup_f32 v2, v3, v2, 1.0
	v_cvt_pk_bf16_f32 v0, v2, v0
	v_fma_f32 v2, -v19, v21, 1.0
	v_fmac_f32_e32 v21, v2, v21
	v_div_scale_f32 v2, vcc, 1.0, v5, 1.0
	v_mul_f32_e32 v3, v2, v21
	v_fma_f32 v18, -v19, v3, v2
	v_fmac_f32_e32 v3, v18, v21
	v_div_scale_f32 v18, s[4:5], v4, v4, 1.0
	v_fma_f32 v2, -v19, v3, v2
	v_rcp_f32_e32 v19, v18
	v_div_fmas_f32 v2, v2, v21, v3
	v_div_fixup_f32 v5, v2, v5, 1.0
	v_div_scale_f32 v20, vcc, 1.0, v4, 1.0
	v_fma_f32 v2, -v18, v19, 1.0
	v_fmac_f32_e32 v19, v2, v19
	v_mul_f32_e32 v21, v20, v19
	v_fma_f32 v2, -v18, v21, v20
	v_fmac_f32_e32 v21, v2, v19
	v_mul_f32_e32 v2, 0xbfb8aa3b, v6
	v_mul_f32_e32 v3, 0xbfb8aa3b, v7
	v_exp_f32_e32 v2, v2
	v_exp_f32_e32 v3, v3
	v_fma_f32 v6, -v18, v21, v20
	v_div_fmas_f32 v6, v6, v19, v21
	v_div_fixup_f32 v4, v6, v4, 1.0
	v_pk_add_f32 v[2:3], v[2:3], 1.0 op_sel_hi:[1,0]
	v_cvt_pk_bf16_f32 v4, v4, v5
	v_div_scale_f32 v7, s[4:5], v3, v3, 1.0
	v_rcp_f32_e32 v18, v7
	v_mov_b32_e32 v177, v0
	v_mov_b32_e32 v178, v4
	v_div_scale_f32 v6, s[4:5], v2, v2, 1.0
	v_fma_f32 v0, -v7, v18, 1.0
	v_fmac_f32_e32 v18, v0, v18
	v_div_scale_f32 v0, vcc, 1.0, v3, 1.0
	v_mul_f32_e32 v4, v0, v18
	v_fma_f32 v5, -v7, v4, v0
	v_fmac_f32_e32 v4, v5, v18
	v_fma_f32 v0, -v7, v4, v0
	v_rcp_f32_e32 v7, v6
	v_div_fmas_f32 v0, v0, v18, v4
	v_mul_f32_e32 v4, 0xbfb8aa3b, v8
	v_mul_f32_e32 v5, 0xbfb8aa3b, v9
	v_div_fixup_f32 v0, v0, v3, 1.0
	v_fma_f32 v3, -v6, v7, 1.0
	v_exp_f32_e32 v4, v4
	v_exp_f32_e32 v5, v5
	v_fmac_f32_e32 v7, v3, v7
	v_div_scale_f32 v3, vcc, 1.0, v2, 1.0
	v_mul_f32_e32 v18, v3, v7
	v_fma_f32 v8, -v6, v18, v3
	v_fmac_f32_e32 v18, v8, v7
	v_pk_add_f32 v[4:5], v[4:5], 1.0 op_sel_hi:[1,0]
	v_fma_f32 v3, -v6, v18, v3
	v_div_scale_f32 v6, s[4:5], v5, v5, 1.0
	v_rcp_f32_e32 v8, v6
	v_div_fmas_f32 v3, v3, v7, v18
	v_div_fixup_f32 v2, v3, v2, 1.0
	v_cvt_pk_bf16_f32 v0, v2, v0
	v_fma_f32 v2, -v6, v8, 1.0
	v_fmac_f32_e32 v8, v2, v8
	v_div_scale_f32 v2, vcc, 1.0, v5, 1.0
	v_mul_f32_e32 v3, v2, v8
	v_fma_f32 v7, -v6, v3, v2
	v_fmac_f32_e32 v3, v7, v8
	v_fma_f32 v2, -v6, v3, v2
	v_div_scale_f32 v6, s[4:5], v4, v4, 1.0
	v_rcp_f32_e32 v7, v6
	v_div_fmas_f32 v2, v2, v8, v3
	v_div_fixup_f32 v5, v2, v5, 1.0
	v_div_scale_f32 v8, vcc, 1.0, v4, 1.0
	v_fma_f32 v2, -v6, v7, 1.0
	v_fmac_f32_e32 v7, v2, v7
	v_mul_f32_e32 v9, v8, v7
	v_fma_f32 v2, -v6, v9, v8
	v_fmac_f32_e32 v9, v2, v7
	v_mul_f32_e32 v2, 0xbfb8aa3b, v10
	v_mul_f32_e32 v3, 0xbfb8aa3b, v11
	v_exp_f32_e32 v2, v2
	v_exp_f32_e32 v3, v3
	v_fma_f32 v6, -v6, v9, v8
	v_div_fmas_f32 v6, v6, v7, v9
	v_div_fixup_f32 v4, v6, v4, 1.0
	v_pk_add_f32 v[2:3], v[2:3], 1.0 op_sel_hi:[1,0]
	v_cvt_pk_bf16_f32 v4, v4, v5
	v_div_scale_f32 v7, s[4:5], v3, v3, 1.0
	v_rcp_f32_e32 v8, v7
	v_mov_b32_e32 v179, v0
	v_mov_b32_e32 v180, v4
	v_div_scale_f32 v6, s[4:5], v2, v2, 1.0
	v_fma_f32 v0, -v7, v8, 1.0
	v_fmac_f32_e32 v8, v0, v8
	v_div_scale_f32 v0, vcc, 1.0, v3, 1.0
	v_mul_f32_e32 v4, v0, v8
	v_fma_f32 v5, -v7, v4, v0
	v_fmac_f32_e32 v4, v5, v8
	v_fma_f32 v0, -v7, v4, v0
	v_rcp_f32_e32 v7, v6
	v_div_fmas_f32 v0, v0, v8, v4
	v_mul_f32_e32 v4, 0xbfb8aa3b, v12
	v_mul_f32_e32 v5, 0xbfb8aa3b, v13
	v_div_fixup_f32 v0, v0, v3, 1.0
	v_fma_f32 v3, -v6, v7, 1.0
	v_exp_f32_e32 v4, v4
	v_exp_f32_e32 v5, v5
	v_fmac_f32_e32 v7, v3, v7
	v_div_scale_f32 v3, vcc, 1.0, v2, 1.0
	v_mul_f32_e32 v8, v3, v7
	v_fma_f32 v9, -v6, v8, v3
	v_fmac_f32_e32 v8, v9, v7
	v_pk_add_f32 v[4:5], v[4:5], 1.0 op_sel_hi:[1,0]
	v_fma_f32 v3, -v6, v8, v3
	v_div_scale_f32 v6, s[4:5], v5, v5, 1.0
	v_rcp_f32_e32 v9, v6
	v_div_fmas_f32 v3, v3, v7, v8
	v_div_fixup_f32 v2, v3, v2, 1.0
	v_cvt_pk_bf16_f32 v0, v2, v0
	v_fma_f32 v2, -v6, v9, 1.0
	v_fmac_f32_e32 v9, v2, v9
	v_div_scale_f32 v2, vcc, 1.0, v5, 1.0
	v_mul_f32_e32 v3, v2, v9
	v_fma_f32 v7, -v6, v3, v2
	v_fmac_f32_e32 v3, v7, v9
	v_fma_f32 v2, -v6, v3, v2
	v_div_scale_f32 v6, s[4:5], v4, v4, 1.0
	v_rcp_f32_e32 v7, v6
	v_div_fmas_f32 v2, v2, v9, v3
	v_div_fixup_f32 v5, v2, v5, 1.0
	v_div_scale_f32 v8, vcc, 1.0, v4, 1.0
	v_fma_f32 v2, -v6, v7, 1.0
	v_fmac_f32_e32 v7, v2, v7
	v_mul_f32_e32 v9, v8, v7
	v_fma_f32 v2, -v6, v9, v8
	v_fmac_f32_e32 v9, v2, v7
	v_mul_f32_e32 v2, 0xbfb8aa3b, v14
	v_mul_f32_e32 v3, 0xbfb8aa3b, v15
	v_exp_f32_e32 v2, v2
	v_exp_f32_e32 v3, v3
	v_fma_f32 v6, -v6, v9, v8
	v_div_fmas_f32 v6, v6, v7, v9
	v_div_fixup_f32 v4, v6, v4, 1.0
	v_pk_add_f32 v[2:3], v[2:3], 1.0 op_sel_hi:[1,0]
	v_cvt_pk_bf16_f32 v4, v4, v5
	v_div_scale_f32 v7, s[4:5], v3, v3, 1.0
	v_rcp_f32_e32 v8, v7
	v_mov_b32_e32 v181, v0
	v_mov_b32_e32 v182, v4
	v_div_scale_f32 v6, s[4:5], v2, v2, 1.0
	v_fma_f32 v0, -v7, v8, 1.0
	v_fmac_f32_e32 v8, v0, v8
	v_div_scale_f32 v0, vcc, 1.0, v3, 1.0
	v_mul_f32_e32 v4, v0, v8
	v_fma_f32 v5, -v7, v4, v0
	v_fmac_f32_e32 v4, v5, v8
	v_fma_f32 v0, -v7, v4, v0
	v_rcp_f32_e32 v7, v6
	v_div_fmas_f32 v0, v0, v8, v4
	v_mul_f32_e32 v4, 0xbfb8aa3b, v16
	v_mul_f32_e32 v5, 0xbfb8aa3b, v17
	v_div_fixup_f32 v0, v0, v3, 1.0
	v_fma_f32 v3, -v6, v7, 1.0
	v_exp_f32_e32 v4, v4
	v_exp_f32_e32 v5, v5
	v_fmac_f32_e32 v7, v3, v7
	v_div_scale_f32 v3, vcc, 1.0, v2, 1.0
	v_mul_f32_e32 v8, v3, v7
	v_fma_f32 v9, -v6, v8, v3
	v_fmac_f32_e32 v8, v9, v7
	v_pk_add_f32 v[4:5], v[4:5], 1.0 op_sel_hi:[1,0]
	v_fma_f32 v3, -v6, v8, v3
	v_div_scale_f32 v6, s[4:5], v5, v5, 1.0
	v_rcp_f32_e32 v9, v6
	v_div_fmas_f32 v3, v3, v7, v8
	v_div_fixup_f32 v2, v3, v2, 1.0
	v_cvt_pk_bf16_f32 v0, v2, v0
	v_fma_f32 v2, -v6, v9, 1.0
	v_fmac_f32_e32 v9, v2, v9
	v_div_scale_f32 v2, vcc, 1.0, v5, 1.0
	v_mul_f32_e32 v3, v2, v9
	v_fma_f32 v7, -v6, v3, v2
	v_fmac_f32_e32 v3, v7, v9
	v_fma_f32 v2, -v6, v3, v2
	v_div_scale_f32 v6, s[4:5], v4, v4, 1.0
	v_rcp_f32_e32 v7, v6
	v_div_fmas_f32 v2, v2, v9, v3
	v_div_fixup_f32 v2, v2, v5, 1.0
	s_or_b32 s4, s6, s13
	v_fma_f32 v3, -v6, v7, 1.0
	v_fmac_f32_e32 v7, v3, v7
	v_div_scale_f32 v3, vcc, 1.0, v4, 1.0
	v_mul_f32_e32 v5, v3, v7
	v_fma_f32 v8, -v6, v5, v3
	v_fmac_f32_e32 v5, v8, v7
	v_fma_f32 v3, -v6, v5, v3
	v_div_fmas_f32 v3, v3, v7, v5
	v_div_fixup_f32 v3, v3, v4, 1.0
	v_cvt_pk_bf16_f32 v2, v3, v2
	v_mov_b32_e32 v3, v133
	v_mov_b32_e32 v183, v0
	v_mov_b32_e32 v213, v2
	s_mov_b32 s15, 0xfffffc0
	v_lshlrev_b32_e32 v0, 3, v3
	v_ashrrev_i32_e32 v4, 3, v3
	v_and_b32_e32 v156, 56, v0
	v_add_u32_e32 v0, 0x100, v3
	v_ashrrev_i32_e32 v5, 3, v0
	v_add_u32_e32 v6, 0x200, v3
	v_mul_lo_u32 v4, v4, s21
	v_ashrrev_i32_e32 v6, 3, v6
	v_add_u32_e32 v7, 0x300, v3
	v_mul_lo_u32 v4, v5, s21
	v_ashrrev_i32_e32 v7, 3, v7
	v_mul_lo_u32 v4, v6, s21
	v_mul_lo_u32 v4, v7, s21
	v_and_b32_e32 v2, 31, v3
	v_add_lshl_u32 v214, v4, v156, 1
	v_lshrrev_b32_e32 v4, 1, v3
	s_add_u32 s4, s42, s4
	v_and_or_b32 v5, v4, s15, v2
	v_and_b32_e32 v2, 16, v4
	s_addc_u32 s5, s43, 0
	s_lshl_b32 s6, s12, 10
	v_mad_u64_u32 v[158:159], s[16:17], v5, s37, v[2:3]
	v_and_b32_e32 v3, 0x5f, v3
	s_add_u32 s6, s9, s6
	v_mad_u32_u24 v159, v3, s37, v2
	v_mov_b32_e32 v2, 0
	s_mov_b32 s14, 1
	s_addc_u32 s7, s10, 0
	v_or_b32_e32 v162, v174, v156
	v_or_b32_e32 v160, v175, v156
	v_or_b32_e32 v0, v176, v156
	v_or_b32_e32 v164, v177, v156
	v_or_b32_e32 v166, v178, v156
	v_or_b32_e32 v168, v179, v156
	v_or_b32_e32 v170, v180, v156
	v_or_b32_e32 v172, v181, v156
	v_mov_b32_e32 v3, v2
	v_mov_b32_e32 v4, v2
	v_mov_b32_e32 v5, v2
	v_mov_b32_e32 v6, v2
	v_mov_b32_e32 v7, v2
	v_mov_b32_e32 v8, v2
	v_mov_b32_e32 v9, v2
	v_mov_b32_e32 v10, v2
	v_mov_b32_e32 v11, v2
	v_mov_b32_e32 v12, v2
	v_mov_b32_e32 v13, v2
	v_mov_b32_e32 v14, v2
	v_mov_b32_e32 v15, v2
	v_mov_b32_e32 v16, v2
	v_mov_b32_e32 v17, v2
	v_mov_b32_e32 v18, v2
	v_mov_b32_e32 v19, v2
	v_mov_b32_e32 v20, v2
	v_mov_b32_e32 v21, v2
	v_mov_b32_e32 v22, v2
	v_mov_b32_e32 v23, v2
	v_mov_b32_e32 v24, v2
	v_mov_b32_e32 v25, v2
	v_mov_b32_e32 v26, v2
	v_mov_b32_e32 v27, v2
	v_mov_b32_e32 v28, v2
	v_mov_b32_e32 v29, v2
	v_mov_b32_e32 v30, v2
	v_mov_b32_e32 v31, v2
	v_mov_b32_e32 v32, v2
	v_mov_b32_e32 v33, v2
	v_mov_b32_e32 v34, v2
	v_mov_b32_e32 v35, v2
	v_mov_b32_e32 v36, v2
	v_mov_b32_e32 v37, v2
	v_mov_b32_e32 v38, v2
	v_mov_b32_e32 v39, v2
	v_mov_b32_e32 v40, v2
	v_mov_b32_e32 v41, v2
	v_mov_b32_e32 v42, v2
	v_mov_b32_e32 v43, v2
	v_mov_b32_e32 v44, v2
	v_mov_b32_e32 v45, v2
	v_mov_b32_e32 v46, v2
	v_mov_b32_e32 v47, v2
	v_mov_b32_e32 v48, v2
	v_mov_b32_e32 v49, v2
	v_mov_b32_e32 v50, v2
	v_mov_b32_e32 v51, v2
	v_mov_b32_e32 v52, v2
	v_mov_b32_e32 v53, v2
	v_mov_b32_e32 v54, v2
	v_mov_b32_e32 v55, v2
	v_mov_b32_e32 v56, v2
	v_mov_b32_e32 v57, v2
	v_mov_b32_e32 v58, v2
	v_mov_b32_e32 v59, v2
	v_mov_b32_e32 v60, v2
	v_mov_b32_e32 v61, v2
	v_mov_b32_e32 v62, v2
	v_mov_b32_e32 v63, v2
	v_mov_b32_e32 v64, v2
	v_mov_b32_e32 v65, v2
	v_and_b32_e32 v236, 63, v133
	v_lshrrev_b32_e32 v237, 6, v133
	v_lshlrev_b32_e32 v238, 12, v237
	v_lshrrev_b32_e32 v239, 3, v236
	v_readfirstlane_b32 s15, v238
	v_lshl_add_u32 v239, v237, 5, v239
	v_and_b32_e32 v240, 7, v236
	v_lshrrev_b32_e32 v241, 4, v236
	v_xor_b32_e32 v240, v240, v241
	v_xor_b32_e32 v241, 4, v240
	v_lshlrev_b32_e32 v240, 4, v240
	v_lshlrev_b32_e32 v241, 4, v241
	v_mul_u32_u24_e32 v242, 0xc00, v239
	v_lshlrev_b32_e32 v243, 10, v239
	v_add_u32_e32 v158, v242, v240
	v_add_u32_e32 v159, v242, v241
	v_add_u32_e32 v159, 0x6000, v159
	v_add_u32_e32 v160, 0xc000, v158
	v_add_u32_e32 v161, 0xc000, v159
	v_add_u32_e32 v162, v243, v240
	v_add_u32_e32 v163, v243, v241
	v_add_u32_e32 v163, 0x2000, v163
	v_add_u32_e32 v164, 0x4000, v162
	v_add_u32_e32 v165, 0x4000, v163
	v_and_b32_e32 v238, 31, v236
	v_lshrrev_b32_e32 v239, 5, v236
	v_bfe_u32 v240, v236, 1, 3
	v_xor_b32_e32 v239, v239, v240
	v_lshrrev_b32_e32 v240, 1, v237
	v_and_b32_e32 v241, 1, v237
	v_lshl_add_u32 v240, v240, 6, v238
	v_lshl_add_u32 v241, v241, 6, v238
	v_lshlrev_b32_e32 v240, 7, v240
	v_lshlrev_b32_e32 v241, 7, v241
	v_add_u32_e32 v241, 0x4000, v241
	v_lshl_add_u32 v166, v239, 4, v240
	v_lshl_add_u32 v170, v239, 4, v241
	v_xor_b32_e32 v242, 2, v239
	v_lshl_add_u32 v167, v242, 4, v240
	v_lshl_add_u32 v171, v242, 4, v241
	v_xor_b32_e32 v242, 4, v239
	v_lshl_add_u32 v168, v242, 4, v240
	v_lshl_add_u32 v172, v242, 4, v241
	v_xor_b32_e32 v242, 6, v239
	v_lshl_add_u32 v169, v242, 4, v240
	v_lshl_add_u32 v173, v242, 4, v241
	s_waitcnt lgkmcnt(0)
	s_barrier
	s_add_u32 m0, s15, 0x0
	s_nop 0
	global_load_lds_dwordx4 v158, s[6:7]
	s_add_u32 m0, s15, 0x400
	s_nop 0
	global_load_lds_dwordx4 v159, s[6:7]
	s_add_u32 m0, s15, 0x800
	s_nop 0
	global_load_lds_dwordx4 v160, s[6:7]
	s_add_u32 m0, s15, 0xc00
	s_nop 0
	global_load_lds_dwordx4 v161, s[6:7]
	s_add_u32 m0, s15, 0x4000
	s_nop 0
	global_load_lds_dwordx4 v162, s[4:5]
	s_add_u32 m0, s15, 0x4400
	s_nop 0
	global_load_lds_dwordx4 v163, s[4:5]
	s_add_u32 m0, s15, 0x4800
	s_nop 0
	global_load_lds_dwordx4 v164, s[4:5]
	s_add_u32 m0, s15, 0x4c00
	s_nop 0
	global_load_lds_dwordx4 v165, s[4:5]
	v_add_u32_e32 v158, 0x80, v158
	v_add_u32_e32 v159, 0x80, v159
	v_add_u32_e32 v160, 0x80, v160
	v_add_u32_e32 v161, 0x80, v161
	v_add_u32_e32 v162, 0x80, v162
	v_add_u32_e32 v163, 0x80, v163
	v_add_u32_e32 v164, 0x80, v164
	v_add_u32_e32 v165, 0x80, v165
	s_mov_b32 s14, 0
	s_waitcnt vmcnt(0)
	.p2alignl 6, 3212836864

.LBB0_176:
	s_or_b64 exec, exec, s[4:5]
	s_waitcnt lgkmcnt(0)
	s_barrier
	ds_read_b32 v0, v186
	s_mov_b32 s76, s73
	s_waitcnt lgkmcnt(0)
	v_readfirstlane_b32 s4, v0
	s_cmp_gt_i32 s4, 31
	s_cbranch_scc1 .LBB0_327
	v_mov_b32_e32 v58, v133
	s_lshl_b32 s4, s4, 2
	v_ashrrev_i32_e32 v59, 6, v58
	v_add_u32_e32 v60, s4, v59
	v_and_b32_e32 v61, 31, v60
	s_waitcnt vmcnt(4)
	v_or_b32_e32 v52, s18, v61
	s_waitcnt vmcnt(1)
	v_ashrrev_i32_e32 v53, 31, v52
	v_lshlrev_b64 v[36:37], 12, v[52:53]
	v_and_b32_e32 v62, 15, v58
	v_readlane_b32 s40, v252, 31
	v_lshl_add_u64 v[16:17], s[86:87], 0, v[36:37]
	v_lshl_or_b32 v36, v62, 8, v36
	v_readlane_b32 s42, v252, 33
	v_readlane_b32 s43, v252, 34
	v_bfe_u32 v64, v58, 5, 1
	v_readlane_b32 s41, v252, 32
	v_lshl_add_u64 v[4:5], s[42:43], 0, v[36:37]
	v_and_b32_e32 v2, 48, v58
	v_mov_b32_e32 v3, v1
	v_and_b32_e32 v63, 31, v58
	v_lshlrev_b32_e32 v0, 4, v64
	v_lshl_add_u64 v[18:19], v[4:5], 0, v[2:3]
	v_lshl_add_u64 v[20:21], v[16:17], 0, v[0:1]
	v_lshlrev_b32_e32 v22, 5, v63
	v_mov_b32_e32 v23, v1
	v_lshl_add_u64 v[36:37], s[40:41], 0, v[36:37]
	global_load_dwordx4 v[4:7], v[18:19], off
	global_load_dwordx4 v[8:11], v[18:19], off offset:64
	global_load_dwordx4 v[12:15], v[18:19], off offset:128
	v_lshl_add_u64 v[32:33], v[20:21], 0, v[22:23]
	global_load_dwordx4 v[16:19], v[18:19], off offset:192
	v_lshl_add_u64 v[48:49], v[36:37], 0, v[2:3]
	global_load_dwordx4 v[20:23], v[32:33], off
	global_load_dwordx4 v[24:27], v[32:33], off offset:1024
	global_load_dwordx4 v[28:31], v[32:33], off offset:2048
	s_nop 0
	global_load_dwordx4 v[32:35], v[32:33], off offset:3072
	s_nop 0
	global_load_dwordx4 v[36:39], v[48:49], off
	global_load_dwordx4 v[40:43], v[48:49], off offset:64
	global_load_dwordx4 v[44:47], v[48:49], off offset:128
	s_nop 0
	global_load_dwordx4 v[48:51], v[48:49], off offset:192
	v_and_b32_e32 v3, 63, v58
	v_lshlrev_b32_e32 v65, 13, v59
	v_lshl_or_b32 v56, v52, 4, v62
	v_lshlrev_b64 v[52:53], 9, v[52:53]
	v_readlane_b32 s44, v252, 35
	v_readlane_b32 s45, v252, 36
	v_mov_b32_e32 v55, v1
	v_lshlrev_b32_e32 v54, 3, v63
	v_lshl_or_b32 v104, v3, 4, v65
	v_ashrrev_i32_e32 v57, 31, v56
	v_lshl_add_u64 v[52:53], s[84:85], 0, v[52:53]
	v_lshl_add_u64 v[56:57], v[56:57], 2, s[44:45]
	v_lshl_add_u64 v[52:53], v[52:53], 0, v[54:55]
	global_load_dwordx2 v[78:79], v[52:53], off
	global_load_dwordx2 v[80:81], v[52:53], off offset:256
	s_waitcnt vmcnt(63) expcnt(7) lgkmcnt(15)
	s_barrier
	global_load_dword v82, v[56:57], off
	v_readlane_b32 s6, v253, 15
	v_readlane_b32 s7, v253, 16
	s_movk_i32 s5, 0x4000
	v_readlane_b32 s46, v252, 37
	v_readlane_b32 s47, v252, 38
	v_readlane_b32 s48, v252, 39
	v_readlane_b32 s49, v252, 40
	v_readlane_b32 s50, v252, 41
	v_readlane_b32 s51, v252, 42
	v_readlane_b32 s52, v252, 43
	v_readlane_b32 s53, v252, 44
	v_readlane_b32 s54, v252, 45
	v_readlane_b32 s55, v252, 46
	s_waitcnt vmcnt(10)
	ds_write_b128 v104, v[20:23] offset:34816
	s_waitcnt vmcnt(8)
	ds_write_b128 v104, v[28:31] offset:35840
	ds_write_b128 v104, v[24:27] offset:36864
	s_waitcnt vmcnt(7)
	ds_write_b128 v104, v[32:35] offset:37888
	v_xor_b32_e32 v3, 0x80000000, v4
	v_xor_b32_e32 v5, 0x80000000, v5
	v_xor_b32_e32 v6, 0x80000000, v6
	v_xor_b32_e32 v7, 0x80000000, v7
	v_xor_b32_e32 v16, 0x80000000, v16
	v_xor_b32_e32 v8, 0x80000000, v8
	v_xor_b32_e32 v9, 0x80000000, v9
	v_xor_b32_e32 v10, 0x80000000, v10
	v_xor_b32_e32 v11, 0x80000000, v11
	v_xor_b32_e32 v12, 0x80000000, v12
	v_xor_b32_e32 v13, 0x80000000, v13
	v_xor_b32_e32 v14, 0x80000000, v14
	v_xor_b32_e32 v15, 0x80000000, v15
	v_xor_b32_e32 v17, 0x80000000, v17
	v_xor_b32_e32 v18, 0x80000000, v18
	v_xor_b32_e32 v19, 0x80000000, v19
	s_waitcnt vmcnt(6)
	v_cvt_pk_bf16_f32 v4, v36, v3
	v_cvt_pk_bf16_f32 v5, v37, v5
	v_cvt_pk_bf16_f32 v6, v38, v6
	v_cvt_pk_bf16_f32 v7, v39, v7
	s_waitcnt vmcnt(3)
	v_cvt_pk_bf16_f32 v16, v48, v16
	v_cvt_pk_bf16_f32 v8, v40, v8
	v_cvt_pk_bf16_f32 v9, v41, v9
	v_cvt_pk_bf16_f32 v10, v42, v10
	v_cvt_pk_bf16_f32 v11, v43, v11
	v_cvt_pk_bf16_f32 v12, v44, v12
	v_cvt_pk_bf16_f32 v13, v45, v13
	v_cvt_pk_bf16_f32 v14, v46, v14
	v_cvt_pk_bf16_f32 v15, v47, v15
	v_cvt_pk_bf16_f32 v17, v49, v17
	v_cvt_pk_bf16_f32 v18, v50, v18
	v_cvt_pk_bf16_f32 v19, v51, v19
	ds_write_b128 v104, v[4:7] offset:38912
	ds_write_b128 v104, v[8:11] offset:39936
	ds_write_b128 v104, v[12:15] offset:40960
	ds_write_b128 v104, v[16:19] offset:41984
	v_lshrrev_b32_e32 v3, 2, v58
	v_ashrrev_i32_e32 v16, 4, v60
	v_bfi_b32 v6, -2, v16, v3
	v_and_b32_e32 v4, 3, v58
	v_lshrrev_b32_e32 v5, 1, v58
	v_ashrrev_i32_e32 v7, 31, v6
	v_and_or_b32 v5, v5, 12, v4
	v_lshlrev_b64 v[6:7], 22, v[6:7]
	v_lshl_add_u64 v[6:7], s[6:7], 0, v[6:7]
	v_lshlrev_b32_e32 v8, 10, v5
	v_mov_b32_e32 v9, v1
	v_and_b32_e32 v4, -2, v16
	v_lshl_add_u64 v[6:7], v[6:7], 0, v[8:9]
	v_lshlrev_b32_e32 v8, 5, v61
	v_lshl_add_u64 v[6:7], v[6:7], 0, v[8:9]
	v_ashrrev_i32_e32 v5, 31, v4
	v_lshl_add_u64 v[84:85], v[6:7], 0, v[0:1]
	v_lshlrev_b64 v[4:5], 22, v[4:5]
	v_lshlrev_b32_e32 v0, 8, v58
	v_lshl_add_u64 v[6:7], s[6:7], 0, v[4:5]
	v_and_b32_e32 v10, 0x3000, v0
	v_mov_b32_e32 v11, v1
	v_lshl_add_u64 v[6:7], v[6:7], 0, v[10:11]
	v_lshl_add_u64 v[6:7], v[6:7], 0, v[8:9]
	v_lshlrev_b32_e32 v0, 1, v62
	v_lshl_add_u64 v[86:87], v[6:7], 0, v[0:1]
	v_add_co_u32_e32 v6, vcc, s5, v84
	s_waitcnt lgkmcnt(0)
	s_nop 0
	v_addc_co_u32_e32 v7, vcc, 0, v85, vcc
	v_add_co_u32_e32 v8, vcc, s5, v86
	s_barrier
	s_nop 0
	v_addc_co_u32_e32 v9, vcc, 0, v87, vcc
	v_add_co_u32_e32 v12, vcc, s70, v86
	global_load_ushort v3, v[86:87], off
	global_load_ushort v11, v[86:87], off offset:1024
	global_load_ushort v17, v[86:87], off offset:2048
	global_load_ushort v18, v[8:9], off
	global_load_ushort v19, v[8:9], off offset:1024
	global_load_ushort v20, v[86:87], off offset:3072
	v_addc_co_u32_e32 v13, vcc, 0, v87, vcc
	s_mov_b32 s5, 0x404000
	v_add_co_u32_e32 v14, vcc, s5, v86
	s_mov_b32 s5, -2
	s_nop 0
	v_addc_co_u32_e32 v15, vcc, 0, v87, vcc
	global_load_ushort v21, v[8:9], off offset:2048
	s_nop 0
	global_load_ushort v8, v[8:9], off offset:3072
	s_nop 0
	global_load_ushort v9, v[12:13], off
	global_load_ushort v22, v[12:13], off offset:1024
	global_load_ushort v23, v[14:15], off
	global_load_ushort v24, v[14:15], off offset:1024
	global_load_ushort v25, v[12:13], off offset:2048
	s_nop 0
	global_load_ushort v12, v[12:13], off offset:3072
	s_nop 0
	global_load_ushort v13, v[14:15], off offset:2048
	s_nop 0
	global_load_ushort v14, v[14:15], off offset:3072
	s_nop 0
	global_load_dwordx4 v[74:77], v[6:7], off
	global_load_dwordx4 v[50:53], v[84:85], off
	s_waitcnt vmcnt(20)
	v_pk_mov_b32 v[88:89], v[78:79], v[78:79] op_sel:[1,0]
	s_waitcnt vmcnt(19)
	v_pk_mov_b32 v[90:91], v[80:81], v[80:81] op_sel:[1,0]
	s_waitcnt vmcnt(16)
	v_perm_b32 v115, v11, v3, s69
	v_lshl_add_u32 v3, v59, 9, v65
	s_waitcnt vmcnt(13)
	v_perm_b32 v111, v19, v18, s69
	s_waitcnt vmcnt(12)
	v_perm_b32 v114, v20, v17, s69
	s_waitcnt vmcnt(10)
	v_perm_b32 v110, v8, v21, s69
	s_waitcnt vmcnt(8)
	v_perm_b32 v113, v22, v9, s69
	s_waitcnt vmcnt(6)
	v_perm_b32 v109, v24, v23, s69
	s_waitcnt vmcnt(4)
	v_perm_b32 v112, v12, v25, s69
	s_waitcnt vmcnt(2)
	v_perm_b32 v108, v14, v13, s69
	s_setprio 1
	v_mul_u32_u24_e32 v6, 0x440, v64
	v_lshl_add_u32 v6, v6, 2, v3
	v_lshl_or_b32 v105, v63, 2, v6
	v_mul_u32_u24_e32 v6, 0x44, v62
	v_or_b32_e32 v7, v3, v2
	v_lshlrev_b32_e32 v6, 2, v6
	v_add_u32_e32 v106, v7, v6
	v_add3_u32 v107, v3, v6, v2
	v_or_b32_e32 v2, 1, v16
	v_add_u16_e32 v6, s4, v59
	v_ashrrev_i32_e32 v3, 31, v2
	v_and_b32_e32 v6, 31, v6
	v_lshlrev_b64 v[2:3], 22, v[2:3]
	v_lshlrev_b32_e32 v6, 5, v6
	v_or3_b32 v2, v2, v10, v6
	v_or3_b32 v4, v4, v10, v6
	v_mov_b32_e32 v96, 0
	v_mov_b32_e32 v83, v82
	v_lshl_add_u64 v[92:93], s[92:93], 0, v[2:3]
	v_lshl_add_u64 v[94:95], s[92:93], 0, v[4:5]
	v_mov_b32_e32 v97, v96
	v_mov_b32_e32 v98, v96
	v_mov_b32_e32 v99, v96
	s_waitcnt vmcnt(0)
	v_mov_b32_e32 v236, 0
	v_mov_b32_e32 v237, 0
	v_mov_b32_e32 v238, 0
	v_mov_b32_e32 v239, 0
	v_xor_b32_e32 v240, 0x80000000, v79
	v_xor_b32_e32 v241, 0x80000000, v81
	.p2alignl 6, 3212836864

.LBB0_182:
	s_lshl_b32 s5, s4, 3
	s_and_b32 s5, s5, 0x7f0
	s_lshr_b32 s6, s4, 7
	s_and_b32 s11, s4, 1
	s_or_b32 s4, s5, s6
	s_lshl_b32 s4, s4, 1
	v_mov_b32_e32 v60, v133
	s_and_b32 s9, s4, 0x1ffffe0
	s_sub_i32 s8, 0xfe0, s9
	v_and_b32_e32 v61, 31, v60
	s_and_b32 s12, s6, 14
	v_or_b32_e32 v126, s8, v61
	v_ashrrev_i32_e32 v23, 6, v60
	s_lshl_b32 s96, s12, 11
	v_ashrrev_i32_e32 v127, 31, v126
	v_lshl_add_u32 v4, s11, 2, v23
	v_lshl_add_u64 v[120:121], v[126:127], 0, s[96:97]
	v_lshlrev_b64 v[2:3], 10, v[120:121]
	v_lshlrev_b32_e32 v122, 6, v4
	v_bfe_u32 v22, v60, 5, 1
	v_lshl_add_u64 v[2:3], s[90:91], 0, v[2:3]
	v_ashrrev_i32_e32 v123, 31, v122
	v_lshl_add_u64 v[2:3], v[122:123], 1, v[2:3]
	v_lshlrev_b32_e32 v0, 4, v22
	v_lshl_add_u64 v[2:3], v[2:3], 0, v[0:1]
	v_readlane_b32 s4, v253, 19
	global_load_dwordx4 v[96:99], v[2:3], off
	global_load_dwordx4 v[100:103], v[2:3], off offset:32
	global_load_dwordx4 v[104:107], v[2:3], off offset:64
	global_load_dwordx4 v[108:111], v[2:3], off offset:96
	v_lshlrev_b64 v[2:3], 7, v[120:121]
	v_readlane_b32 s5, v253, 20
	v_lshl_add_u32 v4, v4, 1, v4
	v_ashrrev_i32_e32 v5, 31, v4
	v_lshl_add_u64 v[2:3], s[4:5], 0, v[2:3]
	v_lshl_add_u64 v[2:3], v[4:5], 2, v[2:3]
	global_load_dwordx3 v[116:118], v[2:3], off
	v_lshlrev_b32_e32 v124, 3, v22
	s_ashr_i32 s10, s8, 9
	s_cmp_gt_i32 s10, -1
	v_lshlrev_b32_e32 v25, 1, v124
	v_mul_u32_u24_e32 v0, 0x90, v61
	s_cselect_b64 s[4:5], -1, 0
	s_cmp_lt_i32 s10, 0
	v_lshlrev_b32_e32 v26, 4, v60
	s_waitcnt vmcnt(8)
	v_subrev_u32_e32 v50, 31, v126
	v_and_b32_e32 v24, 7, v60
	v_ashrrev_i32_e32 v62, 3, v60
	v_add_u32_e32 v63, v25, v0
	s_cbranch_scc1 .LBB0_186
	v_ashrrev_i32_e32 v2, 3, v60
	v_and_b32_e32 v0, 0x70, v26
	v_mad_u64_u32 v[18:19], s[6:7], v2, s37, v[0:1]
	s_add_i32 s6, s12, s11
	v_ashrrev_i32_e32 v3, 31, v2
	s_lshl_b32 s96, s6, 15
	v_lshlrev_b64 v[2:3], 7, v[2:3]
	v_lshl_add_u64 v[2:3], s[96:97], 0, v[2:3]
	v_readlane_b32 s6, v253, 21
	v_lshl_or_b32 v2, v24, 4, v2
	v_readlane_b32 s7, v253, 22
	s_mov_b64 s[14:15], s[66:67]
	v_lshl_or_b32 v0, v22, 6, v201
	v_lshl_add_u64 v[20:21], s[6:7], 0, v[2:3]
	s_add_i32 s6, s10, 1
	v_mov_b32_e32 v6, 0
	v_mov_b32_e32 v19, 0xf149f2ca
	global_load_dwordx4 v[230:233], v[20:21], off
	v_lshl_add_u64 v[20:21], v[20:21], 0, s[94:95]
	.p2alignl 6, 3212836864

.LBB0_187:
	v_cmp_lt_i32_e32 vcc, v194, v193
	v_lshlrev_b32_e32 v4, 3, v60
	s_mov_b64 s[6:7], -1
	v_cndmask_b32_e32 v0, v192, v194, vcc
	v_lshlrev_b32_e32 v119, 2, v0
	ds_bpermute_b32 v2, v119, v19
	ds_bpermute_b32 v3, v119, v6
	s_and_b64 vcc, exec, s[4:5]
	v_and_b32_e32 v64, 56, v4
	s_cbranch_vccz .LBB0_191
	s_waitcnt lgkmcnt(1)
	v_max_f32_e32 v0, v2, v2
	v_max_f32_e32 v5, v19, v19
	v_max_f32_e32 v65, v5, v0
	v_sub_f32_e32 v0, v2, v65
	v_exp_f32_e32 v7, v0
	v_sub_f32_e32 v0, v19, v65
	v_exp_f32_e32 v2, v0
	v_ashrrev_i32_e32 v52, 3, v60
	v_readlane_b32 s6, v253, 23
	v_readlane_b32 s7, v253, 24
	s_waitcnt lgkmcnt(0)
	v_pk_mul_f32 v[2:3], v[6:7], v[2:3]
	s_waitcnt vmcnt(6)
	v_ashrrev_i32_e32 v53, 31, v52
	v_add_f32_e32 v0, v2, v3
	v_div_scale_f32 v2, s[4:5], v0, v0, 1.0
	v_rcp_f32_e32 v3, v2
	s_movk_i32 s4, 0x2400
	s_movk_i32 s5, 0x2080
	v_mov_b32_e32 v67, 0
	v_fma_f32 v5, -v2, v3, 1.0
	v_fmac_f32_e32 v3, v5, v3
	v_div_scale_f32 v5, vcc, 1.0, v0, 1.0
	v_mul_f32_e32 v6, v5, v3
	v_fma_f32 v7, -v2, v6, v5
	v_fmac_f32_e32 v6, v7, v3
	v_fma_f32 v2, -v2, v6, v5
	v_div_fmas_f32 v2, v2, v3, v6
	v_div_fixup_f32 v2, v2, v0, 1.0
	v_cmp_lt_f32_e32 vcc, 0, v0
	v_and_b32_e32 v0, 56, v4
	v_sub_u32_e32 v6, v25, v124
	v_cndmask_b32_e32 v54, 0, v2, vcc
	v_mul_lo_u32 v2, v52, s37
	v_lshl_add_u32 v66, v0, 1, v2
	v_ashrrev_i32_e32 v2, 2, v60
	v_ashrrev_i32_e32 v3, 31, v2
	v_lshlrev_b64 v[4:5], 9, v[2:3]
	v_mul_lo_u32 v2, v2, s37
	v_and_b32_e32 v3, 48, v26
	v_add3_u32 v68, v2, v3, s4
	v_mul_u32_u24_e32 v3, 0x48, v61
	v_lshlrev_b32_e32 v3, 1, v3
	v_add_u32_e32 v69, v6, v3
	v_lshl_or_b32 v70, v22, 3, v3
	v_mul_lo_u32 v3, v23, s5
	s_movk_i32 s5, 0x104
	v_mad_u32_u24 v3, v61, s5, v3
	s_add_i32 s5, s12, s11
	v_lshlrev_b32_e32 v2, 2, v22
	s_lshl_b32 s96, s5, 15
	v_add3_u32 v71, v3, v2, s36
	v_lshl_add_u64 v[2:3], s[96:97], 0, v[4:5]
	v_and_b32_e32 v4, 3, v60
	v_lshl_or_b32 v2, v4, 4, v2
	v_lshl_add_u64 v[56:57], s[6:7], 0, v[2:3]
	v_lshlrev_b64 v[2:3], 7, v[52:53]
	v_lshl_add_u64 v[2:3], s[96:97], 0, v[2:3]
	v_readlane_b32 s6, v253, 21
	v_lshl_or_b32 v2, v24, 4, v2
	v_readlane_b32 s7, v253, 22
	v_cmp_eq_u32_e32 vcc, 0, v22
	v_mov_b32_e32 v51, v50
	v_mov_b32_e32 v55, v54
	s_add_i32 s4, s10, 1
	v_lshlrev_b32_e32 v72, 6, v22
	v_lshl_add_u64 v[58:59], s[6:7], 0, v[2:3]
	v_mov_b32_e32 v2, 0
	v_mov_b32_e32 v3, v67
	v_mov_b32_e32 v4, v67
	v_mov_b32_e32 v5, v67
	v_mov_b32_e32 v6, v67
	v_mov_b32_e32 v7, v67
	v_mov_b32_e32 v8, v67
	v_mov_b32_e32 v9, v67
	v_mov_b32_e32 v10, v67
	v_mov_b32_e32 v11, v67
	v_mov_b32_e32 v12, v67
	v_mov_b32_e32 v13, v67
	v_mov_b32_e32 v14, v67
	v_mov_b32_e32 v15, v67
	v_mov_b32_e32 v16, v67
	v_mov_b32_e32 v17, v67
	v_mov_b32_e32 v18, 0
	v_mov_b32_e32 v19, v67
	v_mov_b32_e32 v20, v67
	v_mov_b32_e32 v21, v67
	v_mov_b32_e32 v22, v67
	v_mov_b32_e32 v23, v67
	v_mov_b32_e32 v24, v67
	v_mov_b32_e32 v25, v67
	v_mov_b32_e32 v26, v67
	v_mov_b32_e32 v27, v67
	v_mov_b32_e32 v28, v67
	v_mov_b32_e32 v29, v67
	v_mov_b32_e32 v30, v67
	v_mov_b32_e32 v31, v67
	v_mov_b32_e32 v32, v67
	v_mov_b32_e32 v33, v67
	global_load_dwordx4 v[230:233], v[58:59], off
	v_lshl_add_u64 v[58:59], v[58:59], 0, s[94:95]
	global_load_dwordx4 v[234:237], v[56:57], off
	v_lshl_add_u64 v[56:57], v[56:57], 0, 64
	.p2alignl 6, 3212836864

.LBB0_281:
	s_or_b64 exec, exec, s[4:5]
	s_waitcnt vmcnt(0)
	v_mul_f32_e32 v34, 0xbfb8aa3b, v116
	v_exp_f32_e32 v34, v34
	v_or_b32_e32 v0, v41, v43
	v_bitop3_b16 v0, v0, v47, v46 bitop3:0xfe
	v_bitop3_b16 v0, v0, v44, v42 bitop3:0xfe
	v_add_f32_e32 v34, 1.0, v34
	v_div_scale_f32 v35, s[4:5], v34, v34, 1.0
	v_rcp_f32_e32 v36, v35
	v_bitop3_b16 v0, v0, v40, v38 bitop3:0xfe
	v_lshlrev_b32_e32 v121, 2, v60
	v_add_u32_e32 v125, 0x10000, v121
	v_fma_f32 v37, -v35, v36, 1.0
	v_fmac_f32_e32 v36, v37, v36
	v_div_scale_f32 v37, vcc, 1.0, v34, 1.0
	v_mul_f32_e32 v39, v37, v36
	v_fma_f32 v41, -v35, v39, v37
	v_fmac_f32_e32 v39, v41, v36
	v_fma_f32 v35, -v35, v39, v37
	v_div_fmas_f32 v35, v35, v36, v39
	v_div_fixup_f32 v34, v35, v34, 1.0
	v_add_u32_e32 v35, 0x13280, v60
	ds_write_b8 v35, v0
	v_lshl_add_u32 v0, v61, 3, v205
	s_waitcnt lgkmcnt(0)
	s_barrier
	ds_read_b64 v[128:129], v0
	v_mul_f32_e32 v0, v34, v2
	v_mul_f32_e32 v3, v34, v3
	v_mul_f32_e32 v2, v34, v18
	ds_write2st64_b32 v121, v0, v3 offset0:144 offset1:148
	v_mul_f32_e32 v0, v34, v19
	ds_write2st64_b32 v121, v2, v0 offset0:208 offset1:212
	v_mul_f32_e32 v0, v34, v4
	v_mul_f32_e32 v3, v34, v5
	v_mul_f32_e32 v2, v34, v20
	ds_write2st64_b32 v121, v0, v3 offset0:152 offset1:156
	v_mul_f32_e32 v0, v34, v21
	ds_write2st64_b32 v121, v2, v0 offset0:216 offset1:220
	v_mul_f32_e32 v0, v34, v6
	v_mul_f32_e32 v3, v34, v7
	v_mul_f32_e32 v2, v34, v22
	ds_write2st64_b32 v121, v0, v3 offset0:160 offset1:164
	v_mul_f32_e32 v0, v34, v23
	ds_write2st64_b32 v121, v2, v0 offset0:224 offset1:228
	v_mul_f32_e32 v0, v34, v8
	v_mul_f32_e32 v3, v34, v9
	v_mul_f32_e32 v2, v34, v24
	ds_write2st64_b32 v121, v0, v3 offset0:168 offset1:172
	v_mul_f32_e32 v0, v34, v25
	ds_write2st64_b32 v121, v2, v0 offset0:232 offset1:236
	v_mul_f32_e32 v0, v34, v10
	v_mul_f32_e32 v3, v34, v11
	v_mul_f32_e32 v2, v34, v26
	ds_write2st64_b32 v121, v0, v3 offset0:176 offset1:180
	v_mul_f32_e32 v0, v34, v27
	ds_write2st64_b32 v121, v2, v0 offset0:240 offset1:244
	v_mul_f32_e32 v0, v34, v12
	v_mul_f32_e32 v3, v34, v13
	v_mul_f32_e32 v2, v34, v28
	ds_write2st64_b32 v121, v0, v3 offset0:184 offset1:188
	v_mul_f32_e32 v0, v34, v29
	ds_write2st64_b32 v121, v2, v0 offset0:248 offset1:252
	v_mul_f32_e32 v2, v34, v30
	v_mul_f32_e32 v0, v34, v14
	ds_write_b32 v125, v2
	v_mul_f32_e32 v2, v34, v15
	ds_write2st64_b32 v121, v0, v2 offset0:192 offset1:196
	v_mul_f32_e32 v0, v34, v31
	v_add_u32_e32 v127, 0x10400, v121
	v_mul_f32_e32 v2, v34, v32
	v_add_u32_e32 v135, 0x10800, v121
	ds_write_b32 v127, v0
	v_mul_f32_e32 v0, v34, v16
	ds_write_b32 v135, v2
	v_mul_f32_e32 v2, v34, v17
	s_or_b32 s11, s12, s11
	ds_write2st64_b32 v121, v0, v2 offset0:200 offset1:204
	v_mul_f32_e32 v0, v34, v33
	v_add_u32_e32 v152, 0x10c00, v121
	v_mov_b32_e32 v2, v133
	ds_write_b32 v152, v0
	s_lshl_b32 s6, s11, 19
	v_readlane_b32 s4, v253, 25
	s_add_u32 s4, s4, s6
	v_ashrrev_i32_e32 v158, 3, v2
	v_add_u32_e32 v0, 0x100, v2
	v_readlane_b32 s5, v253, 26
	v_ashrrev_i32_e32 v160, 3, v0
	v_ashrrev_i32_e32 v159, 31, v158
	v_lshlrev_b32_e32 v0, 3, v2
	s_addc_u32 s5, s5, 0
	v_readlane_b32 s7, v253, 27
	v_lshlrev_b64 v[4:5], 7, v[158:159]
	v_and_b32_e32 v20, 56, v0
	v_ashrrev_i32_e32 v161, 31, v160
	s_add_u32 s6, s7, s6
	v_readlane_b32 s7, v253, 28
	v_lshl_add_u64 v[4:5], s[4:5], 0, v[4:5]
	v_lshlrev_b32_e32 v0, 1, v20
	v_lshlrev_b64 v[8:9], 7, v[160:161]
	s_addc_u32 s7, s7, 0
	v_lshl_add_u64 v[4:5], v[4:5], 0, v[0:1]
	v_lshl_add_u64 v[8:9], s[4:5], 0, v[8:9]
	v_lshlrev_b64 v[12:13], 13, v[158:159]
	global_load_dwordx4 v[4:7], v[4:5], off
	v_lshl_add_u64 v[8:9], v[8:9], 0, v[0:1]
	v_lshl_add_u64 v[12:13], s[6:7], 0, v[12:13]
	v_lshlrev_b64 v[16:17], 13, v[160:161]
	global_load_dwordx4 v[8:11], v[8:9], off
	v_lshl_add_u64 v[162:163], v[12:13], 0, v[0:1]
	v_lshl_add_u64 v[16:17], s[6:7], 0, v[16:17]
	global_load_dwordx4 v[12:15], v[162:163], off
	v_lshl_add_u64 v[164:165], v[16:17], 0, v[0:1]
	global_load_dwordx4 v[16:19], v[164:165], off
	v_mad_u64_u32 v[166:167], s[6:7], v158, s21, v[20:21]
	v_lshlrev_b32_e32 v3, 1, v166
	v_mad_u64_u32 v[168:169], s[6:7], v160, s21, v[20:21]
	s_waitcnt lgkmcnt(0)
	s_barrier
	s_mov_b32 s12, 0
	s_cmp_lt_i32 s10, 0
	s_waitcnt vmcnt(3)
	ds_write_b128 v3, v[4:7]
	v_lshlrev_b32_e32 v4, 1, v168
	s_waitcnt vmcnt(2)
	ds_write_b128 v4, v[8:11]
	s_waitcnt vmcnt(1)
	ds_write_b128 v3, v[12:15] offset:9216
	s_waitcnt vmcnt(0)
	ds_write_b128 v4, v[16:19] offset:9216
	s_waitcnt lgkmcnt(0)
	s_barrier
	s_cbranch_scc1 .LBB0_298
	v_lshl_add_u64 v[170:171], s[4:5], 0, v[0:1]
	v_bfe_u32 v0, v2, 5, 1
	v_and_b32_e32 v116, 31, v2
	v_lshlrev_b32_e32 v131, 4, v0
	v_lshlrev_b32_e32 v2, 2, v0
	v_lshlrev_b32_e32 v0, 3, v0
	v_mov_b32_e32 v14, v1
	v_mov_b32_e32 v15, v1
	v_sub_u32_e32 v159, v126, v2
	v_sub_u32_e32 v161, 0, v0
	v_mov_b32_e32 v0, v1
	v_mov_b32_e32 v2, v1
	v_mov_b32_e32 v3, v1
	v_mov_b32_e32 v4, v1
	v_mov_b32_e32 v5, v1
	v_mov_b32_e32 v6, v1
	v_mov_b32_e32 v7, v1
	v_mov_b32_e32 v8, v1
	v_mov_b32_e32 v9, v1
	v_mov_b32_e32 v10, v1
	v_mov_b32_e32 v11, v1
	v_mov_b32_e32 v12, v1
	v_mov_b32_e32 v13, v1
	v_mov_b64_e32 v[30:31], v[14:15]
	v_mov_b64_e32 v[46:47], v[14:15]
	v_mul_u32_u24_e32 v156, 0x48, v116
	v_mov_b32_e32 v167, 0xf149f2ca
	v_mov_b32_e32 v169, 0
	v_mov_b64_e32 v[28:29], v[12:13]
	v_mov_b64_e32 v[26:27], v[10:11]
	v_mov_b64_e32 v[24:25], v[8:9]
	v_mov_b64_e32 v[22:23], v[6:7]
	v_mov_b64_e32 v[20:21], v[4:5]
	v_mov_b64_e32 v[18:19], v[2:3]
	v_mov_b64_e32 v[16:17], v[0:1]
	v_mov_b64_e32 v[44:45], v[12:13]
	v_mov_b64_e32 v[42:43], v[10:11]
	v_mov_b64_e32 v[40:41], v[8:9]
	v_mov_b64_e32 v[38:39], v[6:7]
	v_mov_b64_e32 v[36:37], v[4:5]
	v_mov_b64_e32 v[34:35], v[2:3]
	v_mov_b64_e32 v[32:33], v[0:1]
	v_lshrrev_b32_e32 v217, 1, v116
	v_xor_b32_e32 v217, v217, v116
	v_and_b32_e32 v217, 4, v217
	v_lshl_add_u32 v217, v217, 1, v217
	v_xor_b32_e32 v217, v217, v116
	s_movk_i32 s4, 0x80
	v_mad_u64_u32 v[190:191], vcc, v158, s4, v[170:171]
	s_mov_b64 s[6:7], 0x800
	v_lshl_add_u64 v[190:191], v[190:191], 0, s[6:7]
	v_mov_b32_e32 v219, v202
	.p2alignl 6, 3212836864

.LBB0_299:
	v_mul_f32_e32 v0, 0xbfb8aa3b, v117
	v_exp_f32_e32 v0, v0
	s_lshl_b32 s4, s11, 18
	s_sub_i32 s5, 0xde1, s9
	s_max_i32 s12, s5, 0
	v_add_f32_e32 v0, 1.0, v0
	v_div_scale_f32 v3, s[6:7], v0, v0, 1.0
	v_rcp_f32_e32 v4, v3
	v_readlane_b32 s5, v253, 30
	v_fma_f32 v5, -v3, v4, 1.0
	v_fmac_f32_e32 v4, v5, v4
	v_div_scale_f32 v5, vcc, 1.0, v0, 1.0
	v_mul_f32_e32 v6, v5, v4
	v_fma_f32 v7, -v3, v6, v5
	v_fmac_f32_e32 v6, v7, v4
	v_fma_f32 v3, -v3, v6, v5
	v_div_fmas_f32 v3, v3, v4, v6
	v_div_fixup_f32 v0, v3, v0, 1.0
	ds_bpermute_b32 v3, v119, v2
	s_waitcnt lgkmcnt(0)
	v_add_f32_e32 v2, v2, v3
	v_div_scale_f32 v3, s[6:7], v2, v2, v0
	v_rcp_f32_e32 v4, v3
	s_lshl_b32 s6, s4, 1
	v_readlane_b32 s4, v253, 29
	s_add_u32 s4, s4, s6
	v_fma_f32 v5, -v3, v4, 1.0
	v_fmac_f32_e32 v4, v5, v4
	v_div_scale_f32 v5, vcc, v0, v2, v0
	v_mul_f32_e32 v6, v5, v4
	v_fma_f32 v7, -v3, v6, v5
	v_fmac_f32_e32 v6, v7, v4
	v_fma_f32 v3, -v3, v6, v5
	v_div_fmas_f32 v3, v3, v4, v6
	v_div_fixup_f32 v0, v3, v2, v0
	ds_read2st64_b32 v[2:3], v121 offset0:144 offset1:148
	ds_read2st64_b32 v[4:5], v121 offset0:208 offset1:212
	s_addc_u32 s5, s5, 0
	v_readlane_b32 s7, v253, 31
	s_add_u32 s6, s7, s6
	s_waitcnt lgkmcnt(1)
	v_fma_f32 v2, v64, v0, v2
	v_fmac_f32_e32 v3, v65, v0
	ds_write2st64_b32 v121, v2, v3 offset0:144 offset1:148
	ds_read2st64_b32 v[2:3], v121 offset0:152 offset1:156
	s_waitcnt lgkmcnt(2)
	v_fma_f32 v4, v48, v0, v4
	v_fmac_f32_e32 v5, v49, v0
	ds_write2st64_b32 v121, v4, v5 offset0:208 offset1:212
	ds_read2st64_b32 v[4:5], v121 offset0:216 offset1:220
	s_waitcnt lgkmcnt(2)
	v_fma_f32 v2, v66, v0, v2
	v_fmac_f32_e32 v3, v67, v0
	ds_write2st64_b32 v121, v2, v3 offset0:152 offset1:156
	ds_read2st64_b32 v[2:3], v121 offset0:160 offset1:164
	s_waitcnt lgkmcnt(2)
	v_fma_f32 v4, v50, v0, v4
	v_fmac_f32_e32 v5, v51, v0
	ds_write2st64_b32 v121, v4, v5 offset0:216 offset1:220
	ds_read2st64_b32 v[4:5], v121 offset0:224 offset1:228
	s_waitcnt lgkmcnt(2)
	v_fma_f32 v2, v68, v0, v2
	v_fmac_f32_e32 v3, v69, v0
	ds_write2st64_b32 v121, v2, v3 offset0:160 offset1:164
	ds_read2st64_b32 v[2:3], v121 offset0:168 offset1:172
	s_waitcnt lgkmcnt(2)
	v_fma_f32 v4, v52, v0, v4
	v_fmac_f32_e32 v5, v53, v0
	ds_write2st64_b32 v121, v4, v5 offset0:224 offset1:228
	ds_read2st64_b32 v[4:5], v121 offset0:232 offset1:236
	s_waitcnt lgkmcnt(2)
	v_fma_f32 v2, v70, v0, v2
	v_fmac_f32_e32 v3, v71, v0
	ds_write2st64_b32 v121, v2, v3 offset0:168 offset1:172
	ds_read2st64_b32 v[2:3], v121 offset0:176 offset1:180
	s_waitcnt lgkmcnt(2)
	v_fma_f32 v4, v54, v0, v4
	v_fmac_f32_e32 v5, v55, v0
	ds_write2st64_b32 v121, v4, v5 offset0:232 offset1:236
	ds_read2st64_b32 v[4:5], v121 offset0:240 offset1:244
	s_waitcnt lgkmcnt(2)
	v_fma_f32 v2, v72, v0, v2
	v_fmac_f32_e32 v3, v73, v0
	ds_write2st64_b32 v121, v2, v3 offset0:176 offset1:180
	ds_read2st64_b32 v[2:3], v121 offset0:184 offset1:188
	s_waitcnt lgkmcnt(2)
	v_fma_f32 v4, v56, v0, v4
	v_fmac_f32_e32 v5, v57, v0
	ds_write2st64_b32 v121, v4, v5 offset0:240 offset1:244
	ds_read2st64_b32 v[4:5], v121 offset0:248 offset1:252
	s_waitcnt lgkmcnt(2)
	v_fma_f32 v2, v74, v0, v2
	v_fmac_f32_e32 v3, v75, v0
	ds_write2st64_b32 v121, v2, v3 offset0:184 offset1:188
	ds_read2st64_b32 v[2:3], v121 offset0:192 offset1:196
	s_waitcnt lgkmcnt(2)
	v_fma_f32 v4, v58, v0, v4
	v_fmac_f32_e32 v5, v59, v0
	ds_write2st64_b32 v121, v4, v5 offset0:248 offset1:252
	ds_read_b32 v4, v125
	s_waitcnt lgkmcnt(2)
	v_fma_f32 v2, v76, v0, v2
	v_fmac_f32_e32 v3, v77, v0
	ds_write2st64_b32 v121, v2, v3 offset0:192 offset1:196
	ds_read_b32 v2, v127
	s_waitcnt lgkmcnt(2)
	v_fmac_f32_e32 v4, v60, v0
	ds_write_b32 v125, v4
	ds_read_b32 v4, v135
	v_readlane_b32 s7, v253, 32
	s_waitcnt lgkmcnt(2)
	v_fmac_f32_e32 v2, v61, v0
	ds_write_b32 v127, v2
	ds_read2st64_b32 v[2:3], v121 offset0:200 offset1:204
	v_mov_b32_e32 v6, v133
	s_addc_u32 s7, s7, 0
	s_lshr_b32 s11, s12, 6
	s_and_b32 s12, s12, 0x3ffffc0
	s_waitcnt lgkmcnt(0)
	v_fma_f32 v2, v78, v0, v2
	v_fmac_f32_e32 v3, v79, v0
	ds_write2st64_b32 v121, v2, v3 offset0:200 offset1:204
	ds_read_b32 v2, v152
	v_fmac_f32_e32 v4, v62, v0
	ds_write_b32 v135, v4
	s_lshl_b32 s96, s12, 1
	s_cmp_gt_i32 s11, s10
	s_waitcnt lgkmcnt(1)
	v_fmac_f32_e32 v2, v63, v0
	ds_write_b32 v152, v2
	s_nop 0
	v_ashrrev_i32_e32 v116, 3, v6
	v_add_u32_e32 v0, 0x100, v6
	v_add_u32_e32 v2, s12, v116
	v_ashrrev_i32_e32 v128, 3, v0
	v_ashrrev_i32_e32 v3, 31, v2
	v_lshlrev_b32_e32 v0, 3, v6
	v_lshlrev_b64 v[2:3], 7, v[2:3]
	v_and_b32_e32 v24, 56, v0
	v_lshl_add_u64 v[2:3], s[4:5], 0, v[2:3]
	v_lshlrev_b32_e32 v0, 1, v24
	v_lshl_add_u64 v[2:3], v[2:3], 0, v[0:1]
	global_load_dwordx4 v[8:11], v[2:3], off
	v_add_u32_e32 v2, s12, v128
	v_ashrrev_i32_e32 v3, 31, v2
	v_lshlrev_b64 v[2:3], 7, v[2:3]
	v_lshl_add_u64 v[2:3], s[4:5], 0, v[2:3]
	v_lshl_add_u64 v[2:3], v[2:3], 0, v[0:1]
	v_ashrrev_i32_e32 v117, 31, v116
	global_load_dwordx4 v[12:15], v[2:3], off
	v_lshlrev_b64 v[2:3], 13, v[116:117]
	v_lshl_add_u64 v[2:3], s[6:7], 0, v[2:3]
	v_lshl_add_u64 v[4:5], v[2:3], 0, s[96:97]
	v_lshl_add_u64 v[4:5], v[4:5], 0, v[0:1]
	v_ashrrev_i32_e32 v129, 31, v128
	global_load_dwordx4 v[16:19], v[4:5], off
	v_lshlrev_b64 v[4:5], 13, v[128:129]
	v_lshl_add_u64 v[4:5], s[6:7], 0, v[4:5]
	v_lshl_add_u64 v[20:21], v[4:5], 0, s[96:97]
	v_lshl_add_u64 v[20:21], v[20:21], 0, v[0:1]
	global_load_dwordx4 v[20:23], v[20:21], off
	v_mad_u64_u32 v[158:159], s[6:7], v116, s21, v[24:25]
	v_lshlrev_b32_e32 v7, 1, v158
	v_mad_u64_u32 v[160:161], s[6:7], v128, s21, v[24:25]
	s_waitcnt lgkmcnt(0)
	s_barrier
	s_waitcnt vmcnt(3)
	ds_write_b128 v7, v[8:11]
	v_lshlrev_b32_e32 v8, 1, v160
	s_waitcnt vmcnt(2)
	ds_write_b128 v8, v[12:15]
	s_waitcnt vmcnt(1)
	ds_write_b128 v7, v[16:19] offset:9216
	s_waitcnt vmcnt(0)
	ds_write_b128 v8, v[20:23] offset:9216
	s_waitcnt lgkmcnt(0)
	s_barrier
	s_cbranch_scc1 .LBB0_316
	v_lshl_add_u64 v[162:163], s[4:5], 0, v[0:1]
	v_lshl_add_u64 v[164:165], v[2:3], 0, v[0:1]
	v_lshl_add_u64 v[166:167], v[4:5], 0, v[0:1]
	v_bfe_u32 v0, v6, 5, 1
	v_lshlrev_b32_e32 v129, 4, v0
	v_lshlrev_b32_e32 v131, 2, v0
	v_lshlrev_b32_e32 v0, 3, v0
	v_mov_b32_e32 v14, v1
	v_mov_b32_e32 v15, v1
	v_and_b32_e32 v117, 31, v6
	v_sub_u32_e32 v161, 0, v0
	v_mov_b32_e32 v0, v1
	v_mov_b32_e32 v2, v1
	v_mov_b32_e32 v3, v1
	v_mov_b32_e32 v4, v1
	v_mov_b32_e32 v5, v1
	v_mov_b32_e32 v6, v1
	v_mov_b32_e32 v7, v1
	v_mov_b32_e32 v8, v1
	v_mov_b32_e32 v9, v1
	v_mov_b32_e32 v10, v1
	v_mov_b32_e32 v11, v1
	v_mov_b32_e32 v12, v1
	v_mov_b32_e32 v13, v1
	v_mov_b64_e32 v[30:31], v[14:15]
	v_mov_b64_e32 v[46:47], v[14:15]
	s_sub_i32 s9, 0xdff, s9
	v_add_u32_e32 v156, 0xfffffe00, v126
	v_mul_u32_u24_e32 v159, 0x48, v117
	v_mov_b32_e32 v168, 0xf149f2ca
	v_mov_b32_e32 v169, 0
	v_mov_b64_e32 v[28:29], v[12:13]
	v_mov_b64_e32 v[26:27], v[10:11]
	v_mov_b64_e32 v[24:25], v[8:9]
	v_mov_b64_e32 v[22:23], v[6:7]
	v_mov_b64_e32 v[20:21], v[4:5]
	v_mov_b64_e32 v[18:19], v[2:3]
	v_mov_b64_e32 v[16:17], v[0:1]
	v_mov_b64_e32 v[44:45], v[12:13]
	v_mov_b64_e32 v[42:43], v[10:11]
	v_mov_b64_e32 v[40:41], v[8:9]
	v_mov_b64_e32 v[38:39], v[6:7]
	v_mov_b64_e32 v[36:37], v[4:5]
	v_mov_b64_e32 v[34:35], v[2:3]
	v_mov_b64_e32 v[32:33], v[0:1]
	s_mov_b32 s12, s11
	v_lshrrev_b32_e32 v218, 1, v117
	v_xor_b32_e32 v218, v218, v117
	v_and_b32_e32 v218, 4, v218
	v_lshl_add_u32 v218, v218, 1, v218
	v_xor_b32_e32 v218, v218, v117
	s_movk_i32 s4, 0x80
	v_mad_u64_u32 v[190:191], vcc, v116, s4, v[162:163]
	s_mov_b64 s[6:7], 0x800
	v_lshl_add_u64 v[190:191], v[190:191], 0, s[6:7]
	v_mov_b32_e32 v219, v202
	.p2alignl 6, 3212836864

.LBB0_332:
	s_or_b64 exec, exec, s[4:5]
	s_waitcnt lgkmcnt(0)
	s_barrier
	ds_read_b32 v0, v186
	s_waitcnt lgkmcnt(0)
	v_readfirstlane_b32 s4, v0
	s_cmpk_gt_i32 s4, 0xff
	s_cbranch_scc1 .LBB0_153
	v_mov_b32_e32 v10, v133
	s_ashr_i32 s8, s4, 5
	v_and_b32_e32 v6, 63, v10
	s_bfe_u32 s6, s4, 0x30002
	s_lshl_b32 s4, s4, 4
	s_and_b32 s5, s4, 48
	v_lshl_or_b32 v2, s6, 6, v6
	s_mul_i32 s4, s78, 0x680
	v_add_u32_e32 v4, s4, v2
	v_readlane_b32 s40, v252, 31
	v_ashrrev_i32_e32 v5, 31, v4
	v_readlane_b32 s52, v252, 43
	v_readlane_b32 s53, v252, 44
	v_readlane_b32 s41, v252, 32
	v_readlane_b32 s42, v252, 33
	v_lshl_add_u64 v[12:13], v[4:5], 2, s[52:53]
	v_add_u32_e32 v4, 0x400, v4
	v_ashrrev_i32_e32 v5, 31, v4
	v_lshl_add_u64 v[4:5], v[4:5], 2, s[52:53]
	v_readlane_b32 s43, v252, 34
	v_readlane_b32 s44, v252, 35
	v_readlane_b32 s45, v252, 36
	v_readlane_b32 s46, v252, 37
	v_readlane_b32 s47, v252, 38
	v_readlane_b32 s48, v252, 39
	v_readlane_b32 s49, v252, 40
	v_readlane_b32 s50, v252, 41
	v_readlane_b32 s51, v252, 42
	v_readlane_b32 s54, v252, 45
	v_readlane_b32 s55, v252, 46
	global_load_dword v3, v[12:13], off
	global_load_dword v16, v[12:13], off offset:2048
	global_load_dword v17, v[4:5], off
	v_or_b32_e32 v4, s19, v2
	v_ashrrev_i32_e32 v7, 6, v10
	v_ashrrev_i32_e32 v5, 31, v4
	v_readlane_b32 s40, v252, 47
	v_lshlrev_b32_e32 v8, 2, v7
	v_lshlrev_b64 v[4:5], 2, v[4:5]
	v_readlane_b32 s46, v252, 53
	v_readlane_b32 s47, v252, 54
	v_readlane_b32 s48, v252, 55
	v_readlane_b32 s49, v252, 56
	v_lshl_add_u64 v[12:13], s[46:47], 0, v[4:5]
	s_ashr_i32 s9, s8, 31
	v_max_i32_e32 v9, 1, v8
	global_load_dword v18, v[12:13], off
	v_lshl_add_u64 v[4:5], s[48:49], 0, v[4:5]
	s_lshl_b64 s[56:57], s[8:9], 12
	v_lshlrev_b32_e32 v0, 1, v2
	v_add_u32_e32 v12, -1, v9
	v_mov_b32_e32 v13, v1
	global_load_dword v19, v[4:5], off
	v_lshl_add_u64 v[4:5], s[88:89], 0, v[0:1]
	v_lshl_add_u64 v[12:13], s[56:57], 0, v[12:13]
	v_mad_u64_u32 v[14:15], s[8:9], v12, s29, v[4:5]
	v_mad_i32_i24 v15, v13, s29, v15
	v_max_i32_e32 v12, 0, v8
	v_mov_b32_e32 v13, v1
	v_lshl_add_u64 v[12:13], s[56:57], 0, v[12:13]
	global_load_ushort v11, v[14:15], off
	global_load_ushort v38, v[14:15], off offset:1024
	global_load_ushort v39, v[14:15], off offset:2048
	v_mad_u64_u32 v[14:15], s[8:9], v12, s29, v[4:5]
	v_max_i32_e32 v9, -1, v8
	v_mad_i32_i24 v15, v13, s29, v15
	v_add_u32_e32 v12, 1, v9
	v_mov_b32_e32 v13, v1
	v_lshl_add_u64 v[12:13], s[56:57], 0, v[12:13]
	global_load_ushort v40, v[14:15], off
	global_load_ushort v41, v[14:15], off offset:1024
	global_load_ushort v42, v[14:15], off offset:2048
	v_mad_u64_u32 v[14:15], s[8:9], v12, s29, v[4:5]
	v_max_i32_e32 v9, -2, v8
	v_mad_i32_i24 v15, v13, s29, v15
	v_add_u32_e32 v12, 2, v9
	v_mov_b32_e32 v13, v1
	v_lshl_add_u64 v[12:13], s[56:57], 0, v[12:13]
	global_load_ushort v54, v[14:15], off
	global_load_ushort v55, v[14:15], off offset:1024
	global_load_ushort v56, v[14:15], off offset:2048
	v_mad_u64_u32 v[14:15], s[8:9], v12, s29, v[4:5]
	v_max_i32_e32 v9, -3, v8
	v_mad_i32_i24 v15, v13, s29, v15
	v_add_u32_e32 v12, 3, v9
	v_mov_b32_e32 v13, v1
	v_lshl_add_u64 v[12:13], s[56:57], 0, v[12:13]
	global_load_ushort v59, v[14:15], off
	global_load_ushort v60, v[14:15], off offset:1024
	global_load_ushort v63, v[14:15], off offset:2048
	v_mad_u64_u32 v[14:15], s[8:9], v12, s29, v[4:5]
	v_ashrrev_i32_e32 v9, 31, v8
	v_mad_i32_i24 v15, v13, s29, v15
	v_lshl_add_u64 v[12:13], s[56:57], 0, v[8:9]
	global_load_ushort v65, v[14:15], off
	global_load_ushort v69, v[14:15], off offset:1024
	global_load_ushort v70, v[14:15], off offset:2048
	v_lshlrev_b64 v[14:15], 10, v[12:13]
	s_lshl_b32 s4, s6, 2
	v_or_b32_e32 v14, v14, v0
	s_add_u32 s58, s64, s4
	v_lshl_add_u64 v[20:21], s[0:1], 0, v[14:15]
	v_lshl_add_u64 v[14:15], s[24:25], 0, v[14:15]
	s_addc_u32 s59, s65, 0
	global_load_ushort v9, v[20:21], off
	v_cmp_gt_i32_e32 vcc, 1, v7
	global_load_ushort v20, v[14:15], off
	v_lshlrev_b64 v[14:15], 5, v[12:13]
	v_lshl_add_u64 v[14:15], s[58:59], 0, v[14:15]
	global_load_dword v21, v[14:15], off
	v_or_b32_e32 v14, 1, v12
	v_mov_b32_e32 v15, v13
	v_lshlrev_b64 v[24:25], 10, v[14:15]
	v_or_b32_e32 v24, v24, v0
	v_lshlrev_b64 v[14:15], 5, v[14:15]
	v_lshl_add_u64 v[22:23], s[0:1], 0, v[24:25]
	v_lshl_add_u64 v[24:25], s[24:25], 0, v[24:25]
	v_lshl_add_u64 v[14:15], s[58:59], 0, v[14:15]
	global_load_ushort v22, v[22:23], off
	v_and_b32_e32 v31, 15, v10
	global_load_ushort v23, v[24:25], off
	s_mov_b32 s4, 0
	global_load_dword v24, v[14:15], off
	v_or_b32_e32 v14, 2, v12
	v_mov_b32_e32 v15, v13
	v_lshlrev_b64 v[26:27], 10, v[14:15]
	v_or_b32_e32 v26, v26, v0
	v_lshlrev_b64 v[14:15], 5, v[14:15]
	v_lshl_add_u64 v[28:29], s[0:1], 0, v[26:27]
	v_lshl_add_u64 v[26:27], s[24:25], 0, v[26:27]
	v_lshl_add_u64 v[14:15], s[58:59], 0, v[14:15]
	v_or_b32_e32 v12, 3, v12
	global_load_ushort v25, v[28:29], off
	v_readlane_b32 s41, v252, 48
	global_load_ushort v27, v[26:27], off
	v_readlane_b32 s42, v252, 49
	global_load_dword v26, v[14:15], off
	v_lshlrev_b64 v[14:15], 10, v[12:13]
	v_or_b32_e32 v14, v14, v0
	v_lshlrev_b64 v[12:13], 5, v[12:13]
	v_lshl_add_u64 v[28:29], s[0:1], 0, v[14:15]
	v_lshl_add_u64 v[14:15], s[24:25], 0, v[14:15]
	v_lshl_add_u64 v[12:13], s[58:59], 0, v[12:13]
	global_load_ushort v28, v[28:29], off
	s_waitcnt vmcnt(24)
	v_cndmask_b32_e64 v62, v11, 0, vcc
	global_load_ushort v29, v[14:15], off
	global_load_dword v30, v[12:13], off
	v_add_u32_e32 v12, 16, v8
	v_max_i32_e32 v13, 1, v12
	v_add_u32_e32 v14, -1, v13
	v_mov_b32_e32 v15, v1
	v_lshl_add_u64 v[14:15], s[56:57], 0, v[14:15]
	v_mad_u64_u32 v[32:33], s[8:9], v14, s29, v[4:5]
	v_mad_i32_i24 v33, v15, s29, v33
	v_max_i32_e32 v14, 0, v12
	v_mov_b32_e32 v15, v1
	v_lshl_add_u64 v[14:15], s[56:57], 0, v[14:15]
	global_load_ushort v71, v[32:33], off
	global_load_ushort v72, v[32:33], off offset:1024
	global_load_ushort v73, v[32:33], off offset:2048
	v_mad_u64_u32 v[32:33], s[8:9], v14, s29, v[4:5]
	v_max_i32_e32 v13, -1, v12
	v_mad_i32_i24 v33, v15, s29, v33
	v_add_u32_e32 v14, 1, v13
	v_mov_b32_e32 v15, v1
	v_lshl_add_u64 v[14:15], s[56:57], 0, v[14:15]
	global_load_ushort v74, v[32:33], off
	global_load_ushort v75, v[32:33], off offset:1024
	global_load_ushort v76, v[32:33], off offset:2048
	v_mad_u64_u32 v[32:33], s[8:9], v14, s29, v[4:5]
	v_max_i32_e32 v13, -2, v12
	v_mad_i32_i24 v33, v15, s29, v33
	v_add_u32_e32 v14, 2, v13
	v_mov_b32_e32 v15, v1
	v_lshl_add_u64 v[14:15], s[56:57], 0, v[14:15]
	global_load_ushort v77, v[32:33], off
	global_load_ushort v83, v[32:33], off offset:1024
	global_load_ushort v84, v[32:33], off offset:2048
	v_mad_u64_u32 v[32:33], s[8:9], v14, s29, v[4:5]
	v_max_i32_e32 v13, -3, v12
	v_mad_i32_i24 v33, v15, s29, v33
	v_add_u32_e32 v14, 3, v13
	v_mov_b32_e32 v15, v1
	v_lshl_add_u64 v[14:15], s[56:57], 0, v[14:15]
	global_load_ushort v85, v[32:33], off
	global_load_ushort v86, v[32:33], off offset:1024
	global_load_ushort v87, v[32:33], off offset:2048
	v_mad_u64_u32 v[32:33], s[8:9], v14, s29, v[4:5]
	v_ashrrev_i32_e32 v13, 31, v12
	v_mad_i32_i24 v33, v15, s29, v33
	v_lshl_add_u64 v[12:13], s[56:57], 0, v[12:13]
	global_load_ushort v90, v[32:33], off
	global_load_ushort v91, v[32:33], off offset:1024
	global_load_ushort v92, v[32:33], off offset:2048
	v_lshlrev_b64 v[32:33], 10, v[12:13]
	v_or_b32_e32 v32, v32, v0
	v_lshl_add_u64 v[14:15], s[0:1], 0, v[32:33]
	v_lshl_add_u64 v[32:33], s[24:25], 0, v[32:33]
	global_load_ushort v15, v[14:15], off
	s_waitcnt vmcnt(41)
	v_cndmask_b32_e64 v67, v38, 0, vcc
	global_load_ushort v43, v[32:33], off
	v_lshlrev_b64 v[32:33], 5, v[12:13]
	v_lshl_add_u64 v[32:33], s[58:59], 0, v[32:33]
	global_load_dword v44, v[32:33], off
	v_or_b32_e32 v32, 1, v12
	v_mov_b32_e32 v33, v13
	v_lshlrev_b64 v[34:35], 10, v[32:33]
	v_or_b32_e32 v34, v34, v0
	v_lshlrev_b64 v[32:33], 5, v[32:33]
	v_lshl_add_u64 v[36:37], s[0:1], 0, v[34:35]
	v_lshl_add_u64 v[34:35], s[24:25], 0, v[34:35]
	v_lshl_add_u64 v[32:33], s[58:59], 0, v[32:33]
	global_load_ushort v48, v[36:37], off
	global_load_ushort v49, v[34:35], off
	global_load_dword v46, v[32:33], off
	v_or_b32_e32 v32, 2, v12
	v_mov_b32_e32 v33, v13
	v_lshlrev_b64 v[34:35], 10, v[32:33]
	v_or_b32_e32 v34, v34, v0
	v_lshlrev_b64 v[32:33], 5, v[32:33]
	v_lshl_add_u64 v[36:37], s[0:1], 0, v[34:35]
	v_lshl_add_u64 v[34:35], s[24:25], 0, v[34:35]
	v_lshl_add_u64 v[32:33], s[58:59], 0, v[32:33]
	v_or_b32_e32 v12, 3, v12
	global_load_ushort v45, v[36:37], off
	global_load_ushort v47, v[34:35], off
	global_load_dword v52, v[32:33], off
	v_lshlrev_b64 v[32:33], 10, v[12:13]
	v_or_b32_e32 v32, v32, v0
	v_lshlrev_b64 v[12:13], 5, v[12:13]
	v_lshl_add_u64 v[34:35], s[0:1], 0, v[32:33]
	v_lshl_add_u64 v[32:33], s[24:25], 0, v[32:33]
	v_lshl_add_u64 v[12:13], s[58:59], 0, v[12:13]
	global_load_ushort v50, v[34:35], off
	global_load_ushort v51, v[32:33], off
	global_load_dword v53, v[12:13], off
	s_waitcnt vmcnt(51)
	v_cndmask_b32_e64 v66, v39, 0, vcc
	v_cmp_gt_i32_e32 vcc, 0, v7
	v_add_u32_e32 v0, s5, v8
	v_bfe_u32 v12, v10, 4, 2
	s_waitcnt vmcnt(50)
	v_cndmask_b32_e64 v89, v40, 0, vcc
	s_waitcnt vmcnt(49)
	v_cndmask_b32_e64 v88, v41, 0, vcc
	s_waitcnt vmcnt(48)
	v_cndmask_b32_e64 v68, v42, 0, vcc
	s_waitcnt vmcnt(47)
	v_cndmask_b32_e64 v61, v54, 0, vcc
	s_waitcnt vmcnt(46)
	v_cndmask_b32_e64 v57, v55, 0, vcc
	s_waitcnt vmcnt(45)
	v_cndmask_b32_e64 v58, v56, 0, vcc
	s_waitcnt vmcnt(44)
	v_cndmask_b32_e64 v64, v59, 0, vcc
	s_waitcnt vmcnt(43)
	v_cndmask_b32_e64 v60, v60, 0, vcc
	s_waitcnt vmcnt(42)
	v_cndmask_b32_e64 v56, v63, 0, vcc
	s_waitcnt vmcnt(41)
	v_cndmask_b32_e64 v55, v65, 0, vcc
	s_waitcnt vmcnt(40)
	v_cndmask_b32_e64 v59, v69, 0, vcc
	s_waitcnt vmcnt(39)
	v_cndmask_b32_e64 v54, v70, 0, vcc
	v_cmp_gt_i32_e32 vcc, -3, v7
	v_or_b32_e32 v10, v0, v12
	v_readlane_b32 s43, v252, 50
	s_waitcnt vmcnt(26)
	v_cndmask_b32_e64 v80, v71, 0, vcc
	s_waitcnt vmcnt(25)
	v_cndmask_b32_e64 v78, v72, 0, vcc
	s_waitcnt vmcnt(24)
	v_cndmask_b32_e64 v79, v73, 0, vcc
	v_cmp_gt_i32_e32 vcc, -4, v7
	v_readlane_b32 s44, v252, 51
	v_readlane_b32 s45, v252, 52
	s_waitcnt vmcnt(23)
	v_cndmask_b32_e64 v82, v74, 0, vcc
	s_waitcnt vmcnt(22)
	v_cndmask_b32_e64 v75, v75, 0, vcc
	s_waitcnt vmcnt(21)
	v_cndmask_b32_e64 v81, v76, 0, vcc
	s_waitcnt vmcnt(20)
	v_cndmask_b32_e64 v76, v77, 0, vcc
	s_waitcnt vmcnt(19)
	v_cndmask_b32_e64 v74, v83, 0, vcc
	s_waitcnt vmcnt(18)
	v_cndmask_b32_e64 v77, v84, 0, vcc
	s_waitcnt vmcnt(17)
	v_cndmask_b32_e64 v72, v85, 0, vcc
	s_waitcnt vmcnt(16)
	v_cndmask_b32_e64 v69, v86, 0, vcc
	s_waitcnt vmcnt(15)
	v_cndmask_b32_e64 v73, v87, 0, vcc
	v_readlane_b32 s50, v252, 57
	s_waitcnt vmcnt(14)
	v_cndmask_b32_e64 v70, v90, 0, vcc
	s_waitcnt vmcnt(13)
	v_cndmask_b32_e64 v14, v91, 0, vcc
	s_waitcnt vmcnt(12)
	v_cndmask_b32_e64 v71, v92, 0, vcc
	v_readlane_b32 s51, v252, 58
	v_readlane_b32 s52, v252, 59
	v_readlane_b32 s53, v252, 60
	v_readlane_b32 s54, v252, 61
	v_readlane_b32 s55, v252, 62
	s_barrier
	s_setprio 1
	v_lshlrev_b32_e32 v0, 2, v6
	v_lshl_or_b32 v32, v7, 10, v0
	s_lshl_b32 s6, s6, 7
	v_or_b32_e32 v0, s5, v12
	s_add_u32 s6, s12, s6
	v_add_lshl_u32 v0, v0, v8, 2
	v_ashrrev_i32_e32 v11, 31, v10
	s_addc_u32 s7, s13, 0
	v_add_u32_e32 v39, 0x3000, v0
	v_lshlrev_b32_e32 v40, 4, v31
	v_add_u32_e32 v41, 0x9000, v0
	v_mov_b32_e32 v0, v1
	v_add_u32_e32 v33, 0x1000, v32
	v_add_u32_e32 v34, 0x2000, v32
	v_add_u32_e32 v35, 0x3000, v32
	v_add_u32_e32 v36, 0x4000, v32
	v_add_u32_e32 v37, 0x5000, v32
	v_add_u32_e32 v38, 32, v8
	v_lshl_add_u64 v[6:7], v[10:11], 1, s[6:7]
	v_or_b32_e32 v42, 0x6000, v40
	v_mov_b64_e32 v[10:11], v[0:1]
	v_mov_b64_e32 v[12:13], v[0:1]
	.p2alignl 6, 3212836864

.LBB0_480:
	s_mul_hi_u32 s5, s4, 0xcccccccd
	s_lshr_b32 s6, s5, 9
	s_mulk_i32 s6, 0x280
	s_sub_i32 s4, s4, s6
	s_lshr_b32 s6, s5, 5
	s_mul_i32 s7, s4, 0xcccd
	s_and_b32 s6, s6, 0x3ffffc0
	s_lshr_b32 s7, s7, 19
	s_add_i32 s6, s6, s7
	s_mul_i32 s7, s7, 10
	s_bfe_u32 s5, s5, 0x20009
	s_sub_i32 s4, s4, s7
	s_mul_i32 s5, s5, 10
	s_and_b32 s4, s4, 0xffff
	s_mul_i32 s6, s6, 40
	s_add_i32 s4, s5, s4
	s_add_i32 s4, s4, s6
	s_mul_hi_u32 s5, s4, 0xcccccccd
	s_lshr_b32 s5, s5, 5
	s_lshl_b32 s96, s5, 8
	s_mul_i32 s5, s5, 40
	s_sub_i32 s7, s4, s5
	s_lshl_b64 s[4:5], s[96:97], 11
	s_add_u32 s38, s0, s4
	v_mov_b32_e32 v0, v133
	s_addc_u32 s39, s1, s5
	s_lshl_b32 s4, s7, 18
	s_add_u32 s40, s14, s4
	v_lshlrev_b32_e32 v2, 3, v0
	v_and_b32_e32 v2, 56, v2
	v_lshlrev_b32_e32 v3, 7, v0
	s_movk_i32 s4, 0xfc00
	v_lshrrev_b32_e32 v4, 1, v0
	v_and_or_b32 v131, v3, s4, v2
	v_lshlrev_b32_e32 v3, 1, v2
	v_and_b32_e32 v2, 0x5f, v0
	v_and_b32_e32 v4, 16, v4
	v_mad_u32_u24 v175, v2, s37, v4
	v_and_b32_e32 v2, 0xfffff9f, v0
	v_mul_lo_u32 v5, v2, s37
	v_lshrrev_b32_e32 v2, 3, v0
	v_mul_lo_u32 v6, v2, s37
	v_add_u32_e32 v2, 0x100, v0
	v_lshrrev_b32_e32 v2, 3, v2
	v_mul_lo_u32 v7, v2, s37
	v_add_u32_e32 v2, 0x200, v0
	v_lshrrev_b32_e32 v2, 3, v2
	v_mul_lo_u32 v8, v2, s37
	v_add_u32_e32 v2, 0x300, v0
	v_lshrrev_b32_e32 v2, 3, v2
	v_mul_lo_u32 v9, v2, s37
	v_add_u32_e32 v2, 0x400, v0
	v_lshrrev_b32_e32 v2, 3, v2
	v_mul_lo_u32 v10, v2, s37
	v_add_u32_e32 v2, 0x500, v0
	v_lshrrev_b32_e32 v2, 3, v2
	v_mul_lo_u32 v11, v2, s37
	v_add_u32_e32 v2, 0x600, v0
	v_lshrrev_b32_e32 v2, 3, v2
	v_mul_lo_u32 v12, v2, s37
	v_add_u32_e32 v2, 0x700, v0
	v_lshrrev_b32_e32 v2, 3, v2
	v_or_b32_e32 v0, 0x60, v0
	v_add_u32_e32 v135, 0x8000, v131
	v_add_u32_e32 v137, 0x10000, v131
	v_add_u32_e32 v152, 0x18000, v131
	v_add_u32_e32 v156, 0x20000, v131
	v_add_u32_e32 v172, 0x28000, v131
	v_add_u32_e32 v173, 0x30000, v131
	v_add_u32_e32 v174, 0x38000, v131
	v_mul_lo_u32 v13, v2, s37
	v_mul_lo_u32 v0, v0, s37
	v_mov_b32_e32 v2, 0
	s_addc_u32 s41, s15, 0
	s_mov_b32 s4, 1
	v_add_u32_e32 v176, v3, v6
	v_add_u32_e32 v177, v3, v7
	v_add_u32_e32 v178, v3, v8
	v_add_u32_e32 v179, v3, v9
	v_add_u32_e32 v180, v3, v10
	v_add_u32_e32 v181, v3, v11
	v_add_u32_e32 v182, v3, v12
	v_add_u32_e32 v183, v3, v13
	v_add_u32_e32 v213, v4, v5
	v_add_u32_e32 v214, v4, v0
	v_mov_b32_e32 v158, v174
	v_mov_b32_e32 v160, v173
	v_mov_b32_e32 v162, v172
	v_mov_b32_e32 v164, v156
	v_mov_b32_e32 v166, v152
	v_mov_b32_e32 v168, v137
	v_mov_b32_e32 v170, v135
	v_mov_b32_e32 v0, v131
	v_mov_b32_e32 v3, v2
	v_mov_b32_e32 v4, v2
	v_mov_b32_e32 v5, v2
	v_mov_b32_e32 v6, v2
	v_mov_b32_e32 v7, v2
	v_mov_b32_e32 v8, v2
	v_mov_b32_e32 v9, v2
	v_mov_b32_e32 v10, v2
	v_mov_b32_e32 v11, v2
	v_mov_b32_e32 v12, v2
	v_mov_b32_e32 v13, v2
	v_mov_b32_e32 v14, v2
	v_mov_b32_e32 v15, v2
	v_mov_b32_e32 v16, v2
	v_mov_b32_e32 v17, v2
	v_mov_b32_e32 v18, v2
	v_mov_b32_e32 v19, v2
	v_mov_b32_e32 v20, v2
	v_mov_b32_e32 v21, v2
	v_mov_b32_e32 v22, v2
	v_mov_b32_e32 v23, v2
	v_mov_b32_e32 v24, v2
	v_mov_b32_e32 v25, v2
	v_mov_b32_e32 v26, v2
	v_mov_b32_e32 v27, v2
	v_mov_b32_e32 v28, v2
	v_mov_b32_e32 v29, v2
	v_mov_b32_e32 v30, v2
	v_mov_b32_e32 v31, v2
	v_mov_b32_e32 v32, v2
	v_mov_b32_e32 v33, v2
	v_mov_b32_e32 v34, v2
	v_mov_b32_e32 v35, v2
	v_mov_b32_e32 v36, v2
	v_mov_b32_e32 v37, v2
	v_mov_b32_e32 v38, v2
	v_mov_b32_e32 v39, v2
	v_mov_b32_e32 v40, v2
	v_mov_b32_e32 v41, v2
	v_mov_b32_e32 v42, v2
	v_mov_b32_e32 v43, v2
	v_mov_b32_e32 v44, v2
	v_mov_b32_e32 v45, v2
	v_mov_b32_e32 v46, v2
	v_mov_b32_e32 v47, v2
	v_mov_b32_e32 v48, v2
	v_mov_b32_e32 v49, v2
	s_waitcnt vmcnt(3)
	v_mov_b32_e32 v50, v2
	s_waitcnt vmcnt(2)
	v_mov_b32_e32 v51, v2
	v_mov_b32_e32 v52, v2
	s_waitcnt vmcnt(1)
	v_mov_b32_e32 v53, v2
	v_mov_b32_e32 v54, v2
	v_mov_b32_e32 v55, v2
	v_mov_b32_e32 v56, v2
	v_mov_b32_e32 v57, v2
	v_mov_b32_e32 v58, v2
	v_mov_b32_e32 v59, v2
	v_mov_b32_e32 v60, v2
	v_mov_b32_e32 v61, v2
	v_mov_b32_e32 v62, v2
	v_mov_b32_e32 v63, v2
	v_mov_b32_e32 v64, v2
	v_mov_b32_e32 v65, v2
	v_mov_b32_e32 v66, v2
	v_mov_b32_e32 v67, v2
	v_mov_b32_e32 v68, v2
	v_mov_b32_e32 v69, v2
	v_mov_b32_e32 v70, v2
	v_mov_b32_e32 v71, v2
	v_mov_b32_e32 v72, v2
	v_mov_b32_e32 v73, v2
	v_mov_b32_e32 v74, v2
	v_mov_b32_e32 v75, v2
	v_mov_b32_e32 v76, v2
	v_mov_b32_e32 v77, v2
	v_mov_b32_e32 v78, v2
	v_mov_b32_e32 v79, v2
	v_mov_b32_e32 v80, v2
	v_mov_b32_e32 v81, v2
	v_mov_b32_e32 v82, v2
	v_mov_b32_e32 v83, v2
	v_mov_b32_e32 v84, v2
	v_mov_b32_e32 v85, v2
	v_mov_b32_e32 v86, v2
	v_mov_b32_e32 v87, v2
	v_mov_b32_e32 v88, v2
	v_mov_b32_e32 v89, v2
	v_mov_b32_e32 v90, v2
	v_mov_b32_e32 v91, v2
	v_mov_b32_e32 v92, v2
	v_mov_b32_e32 v93, v2
	v_mov_b32_e32 v94, v2
	v_mov_b32_e32 v95, v2
	v_mov_b32_e32 v96, v2
	v_mov_b32_e32 v97, v2
	v_mov_b32_e32 v98, v2
	v_mov_b32_e32 v99, v2
	v_mov_b32_e32 v100, v2
	v_mov_b32_e32 v101, v2
	v_mov_b32_e32 v102, v2
	v_mov_b32_e32 v103, v2
	v_mov_b32_e32 v104, v2
	v_mov_b32_e32 v105, v2
	v_mov_b32_e32 v106, v2
	v_mov_b32_e32 v107, v2
	v_mov_b32_e32 v108, v2
	v_mov_b32_e32 v109, v2
	v_mov_b32_e32 v110, v2
	v_mov_b32_e32 v111, v2
	v_mov_b32_e32 v112, v2
	v_mov_b32_e32 v113, v2
	v_mov_b32_e32 v114, v2
	v_mov_b32_e32 v115, v2
	v_mov_b32_e32 v116, v2
	v_mov_b32_e32 v117, v2
	v_mov_b32_e32 v118, v2
	v_mov_b32_e32 v119, v2
	v_mov_b32_e32 v120, v2
	v_mov_b32_e32 v121, v2
	v_mov_b32_e32 v122, v2
	v_mov_b32_e32 v123, v2
	v_mov_b32_e32 v124, v2
	v_mov_b32_e32 v125, v2
	v_mov_b32_e32 v126, v2
	v_mov_b32_e32 v127, v2
	v_mov_b32_e32 v128, v2
	v_mov_b32_e32 v129, v2
	v_and_b32_e32 v0, 63, v133
	v_lshrrev_b32_e32 v170, 6, v133
	v_lshlrev_b32_e32 v171, 10, v170
	v_lshrrev_b32_e32 v169, 2, v0
	v_readfirstlane_b32 s5, v171
	v_lshl_add_u32 v171, v170, 4, v169
	v_lshlrev_b32_e32 v171, 11, v171
	v_and_b32_e32 v166, 3, v0
	v_bfe_u32 v167, v0, 4, 2
	v_xor_b32_e32 v166, v166, v167
	v_lshl_add_u32 v158, v166, 4, v171
	v_add_u32_e32 v159, 0x20000, v158
	v_add_u32_e32 v160, 0x40000, v158
	v_add_u32_e32 v161, 0x60000, v158
	v_and_b32_e32 v166, 31, v0
	v_lshrrev_b32_e32 v167, 5, v0
	v_bfe_u32 v168, v0, 2, 2
	v_xor_b32_e32 v167, v167, v168
	v_lshrrev_b32_e32 v168, 1, v170
	v_and_b32_e32 v169, 1, v170
	v_lshl_add_u32 v168, v168, 7, v166
	v_lshl_add_u32 v169, v169, 6, v166
	v_lshlrev_b32_e32 v168, 6, v168
	v_lshlrev_b32_e32 v169, 6, v169
	v_add_u32_e32 v169, 0x4000, v169
	v_xor_b32_e32 v170, 2, v167
	v_lshl_add_u32 v162, v167, 4, v168
	v_lshl_add_u32 v163, v170, 4, v168
	v_lshl_add_u32 v164, v167, 4, v169
	v_lshl_add_u32 v165, v170, 4, v169
	s_waitcnt lgkmcnt(0)
	s_barrier
	s_add_u32 m0, s5, 0x0
	s_nop 0
	global_load_lds_dwordx4 v158, s[38:39]
	s_add_u32 m0, s5, 0x1000
	s_nop 0
	global_load_lds_dwordx4 v159, s[38:39]
	s_add_u32 m0, s5, 0x2000
	s_nop 0
	global_load_lds_dwordx4 v160, s[38:39]
	s_add_u32 m0, s5, 0x3000
	s_nop 0
	global_load_lds_dwordx4 v161, s[38:39]
	s_add_u32 m0, s5, 0x4000
	s_nop 0
	global_load_lds_dwordx4 v158, s[40:41]
	s_add_u32 m0, s5, 0x5000
	s_nop 0
	global_load_lds_dwordx4 v159, s[40:41]
	v_add_u32_e32 v158, 64, v158
	v_add_u32_e32 v159, 64, v159
	v_add_u32_e32 v160, 64, v160
	v_add_u32_e32 v161, 64, v161
	s_add_u32 m0, s5, 0x6000
	s_nop 0
	global_load_lds_dwordx4 v158, s[38:39]
	s_add_u32 m0, s5, 0x7000
	s_nop 0
	global_load_lds_dwordx4 v159, s[38:39]
	s_add_u32 m0, s5, 0x8000
	s_nop 0
	global_load_lds_dwordx4 v160, s[38:39]
	s_add_u32 m0, s5, 0x9000
	s_nop 0
	global_load_lds_dwordx4 v161, s[38:39]
	s_add_u32 m0, s5, 0xa000
	s_nop 0
	global_load_lds_dwordx4 v158, s[40:41]
	s_add_u32 m0, s5, 0xb000
	s_nop 0
	global_load_lds_dwordx4 v159, s[40:41]
	v_add_u32_e32 v158, 64, v158
	v_add_u32_e32 v159, 64, v159
	v_add_u32_e32 v160, 64, v160
	v_add_u32_e32 v161, 64, v161
	s_mov_b32 s4, 0
	s_waitcnt vmcnt(6)
	.p2alignl 6, 3212836864
